# peeled first K-loop iteration with srcC=0 (no per-unit accumulator zeroing) + residual prefetch in layer-0 down epilogue + attention staging prefetch + prio before barrier
# speedup vs baseline: 1.0124x; 1.0124x over previous
.LBB0_179:
	s_ashr_i32 s47, s46, 31
	s_lshl_b64 s[48:49], s[46:47], 19
	s_add_u32 s48, s26, s48
	s_addc_u32 s49, s27, s49
	s_and_b64 s[50:51], s[44:45], exec
	s_cselect_b32 s47, s49, s63
	s_cselect_b32 s82, s48, s62
	s_ashr_i32 s21, s20, 31
	s_lshl_b64 s[50:51], s[20:21], 19
	s_add_u32 s50, s59, s50
	s_addc_u32 s51, s66, s51
	s_and_b64 s[84:85], s[44:45], exec
	s_cselect_b32 s21, s51, s61
	s_cselect_b32 s83, s50, s60
	s_add_u32 s89, s60, 0x100
	s_addc_u32 s84, s61, 0
	s_add_u32 s60, s62, 0x40080
	s_addc_u32 s61, s63, 0
	s_mov_b32 s85, -2
	s_add_u32 s62, s60, 0xfffc0080
	s_addc_u32 s63, s61, -1
	s_add_i32 s86, 0, 0x10000
	s_cmp_eq_u32 s85, 12
	s_cselect_b32 vcc_hi, s47, s63
	s_cselect_b32 vcc_lo, s82, s62
	v_add_u32_e32 v142, s86, v145
	s_cselect_b32 s63, s21, s84
	s_cselect_b32 s62, s83, s89
	s_add_i32 s92, 0, 0x14000
	ds_read_b128 v[138:141], v142
	ds_read_b128 v[172:175], v142 offset:1024
	ds_read_b128 v[176:179], v142 offset:2048
	ds_read_b128 v[180:183], v142 offset:3072
	v_add_u32_e32 v142, s92, v145
	ds_read_b128 v[184:187], v142
	ds_read_b128 v[188:191], v142 offset:1024
	ds_read_b128 v[192:195], v142 offset:2048
	ds_read_b128 v[196:199], v142 offset:3072
	v_lshl_add_u64 v[142:143], s[60:61], 0, v[136:137]
	s_add_i32 m0, s68, 0xc000
	ds_read_b128 v[210:213], v148
	ds_read_b128 v[214:217], v148 offset:1024
	ds_read_b128 v[218:221], v148 offset:2048
	ds_read_b128 v[224:227], v148 offset:3072
	ds_read_b128 v[228:231], v148 offset:4096
	ds_read_b128 v[232:235], v148 offset:5120
	ds_read_b128 v[236:239], v148 offset:6144
	ds_read_b128 v[240:243], v148 offset:7168
	global_load_lds_dwordx4 v[142:143], off
	v_lshl_add_u64 v[142:143], s[60:61], 0, v[134:135]
	s_add_i32 m0, s68, 0xe000
	s_nop 0
	global_load_lds_dwordx4 v[142:143], off
	s_waitcnt vmcnt(8)
	s_waitcnt lgkmcnt(0)
	s_setprio 1
	s_barrier
	s_waitcnt lgkmcnt(0)
	v_mfma_f32_16x16x32_bf16 v[124:127], v[138:141], v[210:213], 0
	v_mfma_f32_16x16x32_bf16 v[116:119], v[176:179], v[210:213], 0
	v_mfma_f32_16x16x32_bf16 v[108:111], v[138:141], v[218:221], 0
	v_mfma_f32_16x16x32_bf16 v[100:103], v[176:179], v[218:221], 0
	v_mfma_f32_16x16x32_bf16 v[92:95], v[138:141], v[228:231], 0
	v_mfma_f32_16x16x32_bf16 v[84:87], v[176:179], v[228:231], 0
	v_mfma_f32_16x16x32_bf16 v[76:79], v[138:141], v[236:239], 0
	v_mfma_f32_16x16x32_bf16 v[68:71], v[176:179], v[236:239], 0
	v_mfma_f32_16x16x32_bf16 v[124:127], v[172:175], v[214:217], v[124:127]
	v_mfma_f32_16x16x32_bf16 v[116:119], v[180:183], v[214:217], v[116:119]
	v_mfma_f32_16x16x32_bf16 v[108:111], v[172:175], v[224:227], v[108:111]
	v_mfma_f32_16x16x32_bf16 v[100:103], v[180:183], v[224:227], v[100:103]
	v_mfma_f32_16x16x32_bf16 v[92:95], v[172:175], v[232:235], v[92:95]
	v_mfma_f32_16x16x32_bf16 v[84:87], v[180:183], v[232:235], v[84:87]
	v_mfma_f32_16x16x32_bf16 v[76:79], v[172:175], v[240:243], v[76:79]
	v_mfma_f32_16x16x32_bf16 v[68:71], v[180:183], v[240:243], v[68:71]
	s_setprio 0
	s_setprio 1
	v_mfma_f32_16x16x32_bf16 v[120:123], v[184:187], v[210:213], 0
	v_mfma_f32_16x16x32_bf16 v[112:115], v[192:195], v[210:213], 0
	v_mfma_f32_16x16x32_bf16 v[104:107], v[184:187], v[218:221], 0
	v_mfma_f32_16x16x32_bf16 v[96:99], v[192:195], v[218:221], 0
	v_mfma_f32_16x16x32_bf16 v[88:91], v[184:187], v[228:231], 0
	v_mfma_f32_16x16x32_bf16 v[80:83], v[192:195], v[228:231], 0
	v_mfma_f32_16x16x32_bf16 v[72:75], v[184:187], v[236:239], 0
	v_mfma_f32_16x16x32_bf16 v[64:67], v[192:195], v[236:239], 0
	v_mfma_f32_16x16x32_bf16 v[120:123], v[188:191], v[214:217], v[120:123]
	v_mfma_f32_16x16x32_bf16 v[112:115], v[196:199], v[214:217], v[112:115]
	v_mfma_f32_16x16x32_bf16 v[104:107], v[188:191], v[224:227], v[104:107]
	v_mfma_f32_16x16x32_bf16 v[96:99], v[196:199], v[224:227], v[96:99]
	v_mfma_f32_16x16x32_bf16 v[88:91], v[188:191], v[232:235], v[88:91]
	v_mfma_f32_16x16x32_bf16 v[80:83], v[196:199], v[232:235], v[80:83]
	v_mfma_f32_16x16x32_bf16 v[72:75], v[188:191], v[240:243], v[72:75]
	v_mfma_f32_16x16x32_bf16 v[64:67], v[196:199], v[240:243], v[64:67]
	s_setprio 0
	s_barrier
	s_add_i32 s86, s86, s67
	v_lshl_add_u64 v[142:143], s[62:63], 0, v[152:153]
	s_mov_b32 m0, s86
	ds_read_b128 v[210:213], v148 offset:16384
	ds_read_b128 v[214:217], v148 offset:17408
	ds_read_b128 v[218:221], v148 offset:18432
	ds_read_b128 v[224:227], v148 offset:19456
	ds_read_b128 v[228:231], v148 offset:20480
	ds_read_b128 v[232:235], v148 offset:21504
	ds_read_b128 v[236:239], v148 offset:22528
	ds_read_b128 v[240:243], v148 offset:23552
	global_load_lds_dwordx4 v[142:143], off
	s_add_i32 m0, s86, 0x2000
	s_add_u32 s86, s62, 0x40000
	v_lshl_add_u64 v[150:151], s[62:63], 0, v[128:129]
	s_addc_u32 s87, s63, 0
	s_add_i32 s92, s92, s67
	global_load_lds_dwordx4 v[150:151], off
	v_lshl_add_u64 v[244:245], s[86:87], 0, v[152:153]
	s_mov_b32 m0, s92
	v_lshl_add_u64 v[246:247], vcc, 0, v[130:131]
	global_load_lds_dwordx4 v[244:245], off
	v_lshl_add_u64 v[244:245], s[86:87], 0, v[128:129]
	s_add_i32 m0, s92, 0x2000
	s_nop 0
	global_load_lds_dwordx4 v[244:245], off
	v_lshl_add_u64 v[244:245], vcc, 0, v[132:133]
	s_mov_b32 m0, s68
	s_nop 0
	global_load_lds_dwordx4 v[244:245], off
	s_mov_b32 m0, s69
	s_nop 0
	global_load_lds_dwordx4 v[246:247], off
	s_waitcnt vmcnt(8)
	s_waitcnt lgkmcnt(0)
	s_setprio 1
	s_barrier
	s_waitcnt lgkmcnt(0)
	v_mfma_f32_16x16x32_bf16 v[60:63], v[138:141], v[210:213], 0
	v_mfma_f32_16x16x32_bf16 v[52:55], v[176:179], v[210:213], 0
	v_mfma_f32_16x16x32_bf16 v[44:47], v[138:141], v[218:221], 0
	v_mfma_f32_16x16x32_bf16 v[36:39], v[176:179], v[218:221], 0
	v_mfma_f32_16x16x32_bf16 v[28:31], v[138:141], v[228:231], 0
	v_mfma_f32_16x16x32_bf16 v[20:23], v[176:179], v[228:231], 0
	v_mfma_f32_16x16x32_bf16 v[12:15], v[138:141], v[236:239], 0
	v_mfma_f32_16x16x32_bf16 v[4:7], v[176:179], v[236:239], 0
	v_mfma_f32_16x16x32_bf16 v[60:63], v[172:175], v[214:217], v[60:63]
	v_mfma_f32_16x16x32_bf16 v[52:55], v[180:183], v[214:217], v[52:55]
	v_mfma_f32_16x16x32_bf16 v[44:47], v[172:175], v[224:227], v[44:47]
	v_mfma_f32_16x16x32_bf16 v[36:39], v[180:183], v[224:227], v[36:39]
	v_mfma_f32_16x16x32_bf16 v[28:31], v[172:175], v[232:235], v[28:31]
	v_mfma_f32_16x16x32_bf16 v[20:23], v[180:183], v[232:235], v[20:23]
	v_mfma_f32_16x16x32_bf16 v[12:15], v[172:175], v[240:243], v[12:15]
	v_mfma_f32_16x16x32_bf16 v[4:7], v[180:183], v[240:243], v[4:7]
	s_setprio 0
	s_setprio 1
	v_mfma_f32_16x16x32_bf16 v[56:59], v[184:187], v[210:213], 0
	v_mfma_f32_16x16x32_bf16 v[48:51], v[192:195], v[210:213], 0
	v_mfma_f32_16x16x32_bf16 v[40:43], v[184:187], v[218:221], 0
	v_mfma_f32_16x16x32_bf16 v[32:35], v[192:195], v[218:221], 0
	v_mfma_f32_16x16x32_bf16 v[24:27], v[184:187], v[228:231], 0
	v_mfma_f32_16x16x32_bf16 v[16:19], v[192:195], v[228:231], 0
	v_mfma_f32_16x16x32_bf16 v[8:11], v[184:187], v[236:239], 0
	v_mfma_f32_16x16x32_bf16 v[0:3], v[192:195], v[236:239], 0
	v_mfma_f32_16x16x32_bf16 v[56:59], v[188:191], v[214:217], v[56:59]
	v_mfma_f32_16x16x32_bf16 v[48:51], v[196:199], v[214:217], v[48:51]
	v_mfma_f32_16x16x32_bf16 v[40:43], v[188:191], v[224:227], v[40:43]
	v_mfma_f32_16x16x32_bf16 v[32:35], v[196:199], v[224:227], v[32:35]
	v_mfma_f32_16x16x32_bf16 v[24:27], v[188:191], v[232:235], v[24:27]
	v_mfma_f32_16x16x32_bf16 v[16:19], v[196:199], v[232:235], v[16:19]
	v_mfma_f32_16x16x32_bf16 v[8:11], v[188:191], v[240:243], v[8:11]
	v_mfma_f32_16x16x32_bf16 v[0:3], v[196:199], v[240:243], v[0:3]
	s_setprio 0
	s_barrier
	s_add_i32 s92, 0, 0x18000
	v_add_u32_e32 v149, s92, v145
	s_add_i32 s93, 0, 0x1c000
	ds_read_b128 v[138:141], v149
	ds_read_b128 v[172:175], v149 offset:1024
	ds_read_b128 v[176:179], v149 offset:2048
	ds_read_b128 v[180:183], v149 offset:3072
	v_add_u32_e32 v149, s93, v145
	ds_read_b128 v[184:187], v149
	ds_read_b128 v[188:191], v149 offset:1024
	ds_read_b128 v[192:195], v149 offset:2048
	ds_read_b128 v[196:199], v149 offset:3072
	s_add_u32 s86, vcc_lo, 0x40000
	s_addc_u32 s87, vcc_hi, 0
	s_mov_b32 m0, s74
	v_lshl_add_u64 v[248:249], s[86:87], 0, v[132:133]
	ds_read_b128 v[210:213], v148 offset:32768
	ds_read_b128 v[214:217], v148 offset:33792
	ds_read_b128 v[218:221], v148 offset:34816
	ds_read_b128 v[224:227], v148 offset:35840
	ds_read_b128 v[228:231], v148 offset:36864
	ds_read_b128 v[232:235], v148 offset:37888
	ds_read_b128 v[236:239], v148 offset:38912
	ds_read_b128 v[240:243], v148 offset:39936
	global_load_lds_dwordx4 v[248:249], off
	v_lshl_add_u64 v[248:249], s[86:87], 0, v[130:131]
	s_mov_b32 m0, s75
	s_nop 0
	global_load_lds_dwordx4 v[248:249], off
	s_waitcnt vmcnt(8)
	s_waitcnt lgkmcnt(0)
	s_setprio 1
	s_barrier
	s_waitcnt lgkmcnt(0)
	v_mfma_f32_16x16x32_bf16 v[124:127], v[138:141], v[210:213], v[124:127]
	v_mfma_f32_16x16x32_bf16 v[116:119], v[176:179], v[210:213], v[116:119]
	v_mfma_f32_16x16x32_bf16 v[108:111], v[138:141], v[218:221], v[108:111]
	v_mfma_f32_16x16x32_bf16 v[100:103], v[176:179], v[218:221], v[100:103]
	v_mfma_f32_16x16x32_bf16 v[92:95], v[138:141], v[228:231], v[92:95]
	v_mfma_f32_16x16x32_bf16 v[84:87], v[176:179], v[228:231], v[84:87]
	v_mfma_f32_16x16x32_bf16 v[76:79], v[138:141], v[236:239], v[76:79]
	v_mfma_f32_16x16x32_bf16 v[68:71], v[176:179], v[236:239], v[68:71]
	v_mfma_f32_16x16x32_bf16 v[124:127], v[172:175], v[214:217], v[124:127]
	v_mfma_f32_16x16x32_bf16 v[116:119], v[180:183], v[214:217], v[116:119]
	v_mfma_f32_16x16x32_bf16 v[108:111], v[172:175], v[224:227], v[108:111]
	v_mfma_f32_16x16x32_bf16 v[100:103], v[180:183], v[224:227], v[100:103]
	v_mfma_f32_16x16x32_bf16 v[92:95], v[172:175], v[232:235], v[92:95]
	v_mfma_f32_16x16x32_bf16 v[84:87], v[180:183], v[232:235], v[84:87]
	v_mfma_f32_16x16x32_bf16 v[76:79], v[172:175], v[240:243], v[76:79]
	v_mfma_f32_16x16x32_bf16 v[68:71], v[180:183], v[240:243], v[68:71]
	s_setprio 0
	s_setprio 1
	v_mfma_f32_16x16x32_bf16 v[120:123], v[184:187], v[210:213], v[120:123]
	v_mfma_f32_16x16x32_bf16 v[112:115], v[192:195], v[210:213], v[112:115]
	v_mfma_f32_16x16x32_bf16 v[104:107], v[184:187], v[218:221], v[104:107]
	v_mfma_f32_16x16x32_bf16 v[96:99], v[192:195], v[218:221], v[96:99]
	v_mfma_f32_16x16x32_bf16 v[88:91], v[184:187], v[228:231], v[88:91]
	v_mfma_f32_16x16x32_bf16 v[80:83], v[192:195], v[228:231], v[80:83]
	v_mfma_f32_16x16x32_bf16 v[72:75], v[184:187], v[236:239], v[72:75]
	v_mfma_f32_16x16x32_bf16 v[64:67], v[192:195], v[236:239], v[64:67]
	v_mfma_f32_16x16x32_bf16 v[120:123], v[188:191], v[214:217], v[120:123]
	v_mfma_f32_16x16x32_bf16 v[112:115], v[196:199], v[214:217], v[112:115]
	v_mfma_f32_16x16x32_bf16 v[104:107], v[188:191], v[224:227], v[104:107]
	v_mfma_f32_16x16x32_bf16 v[96:99], v[196:199], v[224:227], v[96:99]
	v_mfma_f32_16x16x32_bf16 v[88:91], v[188:191], v[232:235], v[88:91]
	v_mfma_f32_16x16x32_bf16 v[80:83], v[196:199], v[232:235], v[80:83]
	v_mfma_f32_16x16x32_bf16 v[72:75], v[188:191], v[240:243], v[72:75]
	v_mfma_f32_16x16x32_bf16 v[64:67], v[196:199], v[240:243], v[64:67]
	s_setprio 0
	s_barrier
	s_add_i32 s86, s92, s67
	v_lshl_add_u64 v[142:143], v[142:143], 0, s[22:23]
	s_mov_b32 m0, s86
	ds_read_b128 v[210:213], v148 offset:49152
	ds_read_b128 v[214:217], v148 offset:50176
	ds_read_b128 v[218:221], v148 offset:51200
	ds_read_b128 v[224:227], v148 offset:52224
	ds_read_b128 v[228:231], v148 offset:53248
	ds_read_b128 v[232:235], v148 offset:54272
	ds_read_b128 v[236:239], v148 offset:55296
	ds_read_b128 v[240:243], v148 offset:56320
	global_load_lds_dwordx4 v[142:143], off
	s_add_i32 m0, s86, 0x2000
	s_add_u32 s62, s62, 0x40080
	v_lshl_add_u64 v[142:143], v[150:151], 0, s[22:23]
	s_addc_u32 s63, s63, 0
	s_add_i32 s86, s93, s67
	global_load_lds_dwordx4 v[142:143], off
	v_lshl_add_u64 v[142:143], s[62:63], 0, v[152:153]
	s_mov_b32 m0, s86
	s_nop 0
	global_load_lds_dwordx4 v[142:143], off
	v_lshl_add_u64 v[142:143], s[62:63], 0, v[128:129]
	s_add_i32 m0, s86, 0x2000
	s_nop 0
	global_load_lds_dwordx4 v[142:143], off
	v_lshl_add_u64 v[142:143], v[244:245], 0, s[22:23]
	s_mov_b32 m0, s77
	s_nop 0
	global_load_lds_dwordx4 v[142:143], off
	v_lshl_add_u64 v[142:143], v[246:247], 0, s[22:23]
	s_mov_b32 m0, s78
	s_nop 0
	global_load_lds_dwordx4 v[142:143], off
	s_waitcnt vmcnt(8)
	s_waitcnt lgkmcnt(0)
	s_setprio 1
	s_barrier
	s_waitcnt lgkmcnt(0)
	v_mfma_f32_16x16x32_bf16 v[60:63], v[138:141], v[210:213], v[60:63]
	v_mfma_f32_16x16x32_bf16 v[52:55], v[176:179], v[210:213], v[52:55]
	v_mfma_f32_16x16x32_bf16 v[44:47], v[138:141], v[218:221], v[44:47]
	v_mfma_f32_16x16x32_bf16 v[36:39], v[176:179], v[218:221], v[36:39]
	v_mfma_f32_16x16x32_bf16 v[28:31], v[138:141], v[228:231], v[28:31]
	v_mfma_f32_16x16x32_bf16 v[20:23], v[176:179], v[228:231], v[20:23]
	v_mfma_f32_16x16x32_bf16 v[12:15], v[138:141], v[236:239], v[12:15]
	v_mfma_f32_16x16x32_bf16 v[4:7], v[176:179], v[236:239], v[4:7]
	v_mfma_f32_16x16x32_bf16 v[60:63], v[172:175], v[214:217], v[60:63]
	v_mfma_f32_16x16x32_bf16 v[52:55], v[180:183], v[214:217], v[52:55]
	v_mfma_f32_16x16x32_bf16 v[44:47], v[172:175], v[224:227], v[44:47]
	v_mfma_f32_16x16x32_bf16 v[36:39], v[180:183], v[224:227], v[36:39]
	v_mfma_f32_16x16x32_bf16 v[28:31], v[172:175], v[232:235], v[28:31]
	v_mfma_f32_16x16x32_bf16 v[20:23], v[180:183], v[232:235], v[20:23]
	v_mfma_f32_16x16x32_bf16 v[12:15], v[172:175], v[240:243], v[12:15]
	v_mfma_f32_16x16x32_bf16 v[4:7], v[180:183], v[240:243], v[4:7]
	s_setprio 0
	s_setprio 1
	v_mfma_f32_16x16x32_bf16 v[56:59], v[184:187], v[210:213], v[56:59]
	v_mfma_f32_16x16x32_bf16 v[48:51], v[192:195], v[210:213], v[48:51]
	v_mfma_f32_16x16x32_bf16 v[40:43], v[184:187], v[218:221], v[40:43]
	v_mfma_f32_16x16x32_bf16 v[32:35], v[192:195], v[218:221], v[32:35]
	v_mfma_f32_16x16x32_bf16 v[24:27], v[184:187], v[228:231], v[24:27]
	v_mfma_f32_16x16x32_bf16 v[16:19], v[192:195], v[228:231], v[16:19]
	v_mfma_f32_16x16x32_bf16 v[8:11], v[184:187], v[236:239], v[8:11]
	v_mfma_f32_16x16x32_bf16 v[0:3], v[192:195], v[236:239], v[0:3]
	v_mfma_f32_16x16x32_bf16 v[56:59], v[188:191], v[214:217], v[56:59]
	v_mfma_f32_16x16x32_bf16 v[48:51], v[196:199], v[214:217], v[48:51]
	v_mfma_f32_16x16x32_bf16 v[40:43], v[188:191], v[224:227], v[40:43]
	v_mfma_f32_16x16x32_bf16 v[32:35], v[196:199], v[224:227], v[32:35]
	v_mfma_f32_16x16x32_bf16 v[24:27], v[188:191], v[232:235], v[24:27]
	v_mfma_f32_16x16x32_bf16 v[16:19], v[196:199], v[232:235], v[16:19]
	v_mfma_f32_16x16x32_bf16 v[8:11], v[188:191], v[240:243], v[8:11]
	v_mfma_f32_16x16x32_bf16 v[0:3], v[196:199], v[240:243], v[0:3]
	s_setprio 0
	s_barrier
	s_add_i32 s85, s85, 2
	s_add_u32 s89, s89, 0x100
	s_addc_u32 s84, s84, 0
	s_add_u32 s60, s60, 0x100
	s_addc_u32 s61, s61, 0
	s_cmp_gt_u32 s85, 13

.LBB0_280:
	s_add_u32 s84, s18, 0x100
	s_addc_u32 s85, s19, 0
	s_mov_b32 s86, -2
	s_waitcnt lgkmcnt(0)
	s_add_u32 vcc_lo, s60, 0x100
	s_addc_u32 vcc_hi, s61, 0
	s_add_i32 s87, 0, 0x10000
	s_cmp_eq_u32 s86, 40
	s_cselect_b32 s67, s51, vcc_hi
	s_cselect_b32 s66, s50, vcc_lo
	s_cselect_b32 s19, s45, s85
	s_cselect_b32 s18, s44, s84
	s_add_i32 s92, 0, 0x14000
	v_add_u32_e32 v140, s87, v210
	v_add_u32_e32 v186, s92, v210
	ds_read_b128 v[128:131], v140
	ds_read_b128 v[132:135], v140 offset:1024
	ds_read_b128 v[136:139], v140 offset:2048
	ds_read_b128 v[140:143], v140 offset:3072
	ds_read_b128 v[144:147], v186
	ds_read_b128 v[148:151], v186 offset:1024
	ds_read_b128 v[182:185], v186 offset:2048
	ds_read_b128 v[186:189], v186 offset:3072
	v_lshl_add_u64 v[198:199], s[60:61], 0, v[180:181]
	s_add_i32 m0, s69, 0xc000
	ds_read_b128 v[190:193], v212
	ds_read_b128 v[194:197], v212 offset:1024
	ds_read_b128 v[214:217], v212 offset:2048
	ds_read_b128 v[218:221], v212 offset:3072
	ds_read_b128 v[224:227], v212 offset:4096
	ds_read_b128 v[228:231], v212 offset:5120
	ds_read_b128 v[232:235], v212 offset:6144
	ds_read_b128 v[236:239], v212 offset:7168
	global_load_lds_dwordx4 v[198:199], off
	v_lshl_add_u64 v[198:199], s[60:61], 0, v[178:179]
	s_add_i32 m0, s69, 0xe000
	s_nop 0
	global_load_lds_dwordx4 v[198:199], off
	s_waitcnt vmcnt(8)
	s_waitcnt lgkmcnt(0)
	s_setprio 1
	s_barrier
	s_waitcnt lgkmcnt(0)
	v_mfma_f32_16x16x32_bf16 v[124:127], v[128:131], v[190:193], 0
	v_mfma_f32_16x16x32_bf16 v[120:123], v[136:139], v[190:193], 0
	v_mfma_f32_16x16x32_bf16 v[108:111], v[128:131], v[214:217], 0
	v_mfma_f32_16x16x32_bf16 v[104:107], v[136:139], v[214:217], 0
	v_mfma_f32_16x16x32_bf16 v[92:95], v[128:131], v[224:227], 0
	v_mfma_f32_16x16x32_bf16 v[88:91], v[136:139], v[224:227], 0
	v_mfma_f32_16x16x32_bf16 v[76:79], v[128:131], v[232:235], 0
	v_mfma_f32_16x16x32_bf16 v[72:75], v[136:139], v[232:235], 0
	v_mfma_f32_16x16x32_bf16 v[124:127], v[132:135], v[194:197], v[124:127]
	v_mfma_f32_16x16x32_bf16 v[120:123], v[140:143], v[194:197], v[120:123]
	v_mfma_f32_16x16x32_bf16 v[108:111], v[132:135], v[218:221], v[108:111]
	v_mfma_f32_16x16x32_bf16 v[104:107], v[140:143], v[218:221], v[104:107]
	v_mfma_f32_16x16x32_bf16 v[92:95], v[132:135], v[228:231], v[92:95]
	v_mfma_f32_16x16x32_bf16 v[88:91], v[140:143], v[228:231], v[88:91]
	v_mfma_f32_16x16x32_bf16 v[76:79], v[132:135], v[236:239], v[76:79]
	v_mfma_f32_16x16x32_bf16 v[72:75], v[140:143], v[236:239], v[72:75]
	s_setprio 0
	s_setprio 1
	v_mfma_f32_16x16x32_bf16 v[116:119], v[144:147], v[190:193], 0
	v_mfma_f32_16x16x32_bf16 v[112:115], v[182:185], v[190:193], 0
	v_mfma_f32_16x16x32_bf16 v[100:103], v[144:147], v[214:217], 0
	v_mfma_f32_16x16x32_bf16 v[96:99], v[182:185], v[214:217], 0
	v_mfma_f32_16x16x32_bf16 v[84:87], v[144:147], v[224:227], 0
	v_mfma_f32_16x16x32_bf16 v[80:83], v[182:185], v[224:227], 0
	v_mfma_f32_16x16x32_bf16 v[68:71], v[144:147], v[232:235], 0
	v_mfma_f32_16x16x32_bf16 v[64:67], v[182:185], v[232:235], 0
	v_mfma_f32_16x16x32_bf16 v[116:119], v[148:151], v[194:197], v[116:119]
	v_mfma_f32_16x16x32_bf16 v[112:115], v[186:189], v[194:197], v[112:115]
	v_mfma_f32_16x16x32_bf16 v[100:103], v[148:151], v[218:221], v[100:103]
	v_mfma_f32_16x16x32_bf16 v[96:99], v[186:189], v[218:221], v[96:99]
	v_mfma_f32_16x16x32_bf16 v[84:87], v[148:151], v[228:231], v[84:87]
	v_mfma_f32_16x16x32_bf16 v[80:83], v[186:189], v[228:231], v[80:83]
	v_mfma_f32_16x16x32_bf16 v[68:71], v[148:151], v[236:239], v[68:71]
	v_mfma_f32_16x16x32_bf16 v[64:67], v[186:189], v[236:239], v[64:67]
	s_setprio 0
	s_barrier
	s_add_i32 s60, s87, s68
	v_lshl_add_u64 v[198:199], s[18:19], 0, v[152:153]
	s_mov_b32 m0, s60
	ds_read_b128 v[190:193], v212 offset:16384
	ds_read_b128 v[194:197], v212 offset:17408
	ds_read_b128 v[214:217], v212 offset:18432
	ds_read_b128 v[218:221], v212 offset:19456
	ds_read_b128 v[224:227], v212 offset:20480
	ds_read_b128 v[228:231], v212 offset:21504
	ds_read_b128 v[232:235], v212 offset:22528
	ds_read_b128 v[236:239], v212 offset:23552
	global_load_lds_dwordx4 v[198:199], off
	s_add_i32 m0, s60, 0x2000
	s_add_u32 s60, s18, 0xb0000
	v_lshl_add_u64 v[240:241], s[18:19], 0, v[172:173]
	s_addc_u32 s61, s19, 0
	s_add_i32 s87, s92, s68
	global_load_lds_dwordx4 v[240:241], off
	v_lshl_add_u64 v[242:243], s[60:61], 0, v[152:153]
	s_mov_b32 m0, s87
	v_lshl_add_u64 v[244:245], s[66:67], 0, v[174:175]
	global_load_lds_dwordx4 v[242:243], off
	v_lshl_add_u64 v[242:243], s[60:61], 0, v[172:173]
	s_add_i32 m0, s87, 0x2000
	s_nop 0
	global_load_lds_dwordx4 v[242:243], off
	v_lshl_add_u64 v[242:243], s[66:67], 0, v[176:177]
	s_mov_b32 m0, s69
	s_nop 0
	global_load_lds_dwordx4 v[242:243], off
	s_mov_b32 m0, s74
	s_nop 0
	global_load_lds_dwordx4 v[244:245], off
	s_waitcnt vmcnt(8)
	s_waitcnt lgkmcnt(0)
	s_setprio 1
	s_barrier
	s_waitcnt lgkmcnt(0)
	v_mfma_f32_16x16x32_bf16 v[60:63], v[128:131], v[190:193], 0
	v_mfma_f32_16x16x32_bf16 v[56:59], v[136:139], v[190:193], 0
	v_mfma_f32_16x16x32_bf16 v[44:47], v[128:131], v[214:217], 0
	v_mfma_f32_16x16x32_bf16 v[40:43], v[136:139], v[214:217], 0
	v_mfma_f32_16x16x32_bf16 v[28:31], v[128:131], v[224:227], 0
	v_mfma_f32_16x16x32_bf16 v[24:27], v[136:139], v[224:227], 0
	v_mfma_f32_16x16x32_bf16 v[12:15], v[128:131], v[232:235], 0
	v_mfma_f32_16x16x32_bf16 v[8:11], v[136:139], v[232:235], 0
	v_mfma_f32_16x16x32_bf16 v[60:63], v[132:135], v[194:197], v[60:63]
	v_mfma_f32_16x16x32_bf16 v[56:59], v[140:143], v[194:197], v[56:59]
	v_mfma_f32_16x16x32_bf16 v[44:47], v[132:135], v[218:221], v[44:47]
	v_mfma_f32_16x16x32_bf16 v[40:43], v[140:143], v[218:221], v[40:43]
	v_mfma_f32_16x16x32_bf16 v[28:31], v[132:135], v[228:231], v[28:31]
	v_mfma_f32_16x16x32_bf16 v[24:27], v[140:143], v[228:231], v[24:27]
	v_mfma_f32_16x16x32_bf16 v[12:15], v[132:135], v[236:239], v[12:15]
	v_mfma_f32_16x16x32_bf16 v[8:11], v[140:143], v[236:239], v[8:11]
	s_setprio 0
	s_setprio 1
	v_mfma_f32_16x16x32_bf16 v[52:55], v[144:147], v[190:193], 0
	v_mfma_f32_16x16x32_bf16 v[48:51], v[182:185], v[190:193], 0
	v_mfma_f32_16x16x32_bf16 v[36:39], v[144:147], v[214:217], 0
	v_mfma_f32_16x16x32_bf16 v[32:35], v[182:185], v[214:217], 0
	v_mfma_f32_16x16x32_bf16 v[20:23], v[144:147], v[224:227], 0
	v_mfma_f32_16x16x32_bf16 v[16:19], v[182:185], v[224:227], 0
	v_mfma_f32_16x16x32_bf16 v[4:7], v[144:147], v[232:235], 0
	v_mfma_f32_16x16x32_bf16 v[0:3], v[182:185], v[232:235], 0
	v_mfma_f32_16x16x32_bf16 v[52:55], v[148:151], v[194:197], v[52:55]
	v_mfma_f32_16x16x32_bf16 v[48:51], v[186:189], v[194:197], v[48:51]
	v_mfma_f32_16x16x32_bf16 v[36:39], v[148:151], v[218:221], v[36:39]
	v_mfma_f32_16x16x32_bf16 v[32:35], v[186:189], v[218:221], v[32:35]
	v_mfma_f32_16x16x32_bf16 v[20:23], v[148:151], v[228:231], v[20:23]
	v_mfma_f32_16x16x32_bf16 v[16:19], v[186:189], v[228:231], v[16:19]
	v_mfma_f32_16x16x32_bf16 v[4:7], v[148:151], v[236:239], v[4:7]
	v_mfma_f32_16x16x32_bf16 v[0:3], v[186:189], v[236:239], v[0:3]
	s_setprio 0
	s_barrier
	s_add_i32 s87, 0, 0x18000
	s_add_i32 s92, 0, 0x1c000
	v_add_u32_e32 v140, s87, v210
	v_add_u32_e32 v186, s92, v210
	ds_read_b128 v[128:131], v140
	ds_read_b128 v[132:135], v140 offset:1024
	ds_read_b128 v[136:139], v140 offset:2048
	ds_read_b128 v[140:143], v140 offset:3072
	ds_read_b128 v[144:147], v186
	ds_read_b128 v[148:151], v186 offset:1024
	ds_read_b128 v[182:185], v186 offset:2048
	ds_read_b128 v[186:189], v186 offset:3072
	s_add_u32 s60, s66, 0xb0000
	s_addc_u32 s61, s67, 0
	s_mov_b32 m0, s75
	v_lshl_add_u64 v[246:247], s[60:61], 0, v[176:177]
	ds_read_b128 v[190:193], v212 offset:32768
	ds_read_b128 v[194:197], v212 offset:33792
	ds_read_b128 v[214:217], v212 offset:34816
	ds_read_b128 v[218:221], v212 offset:35840
	ds_read_b128 v[224:227], v212 offset:36864
	ds_read_b128 v[228:231], v212 offset:37888
	ds_read_b128 v[232:235], v212 offset:38912
	ds_read_b128 v[236:239], v212 offset:39936
	global_load_lds_dwordx4 v[246:247], off
	v_lshl_add_u64 v[246:247], s[60:61], 0, v[174:175]
	s_mov_b32 m0, s76
	s_nop 0
	global_load_lds_dwordx4 v[246:247], off
	s_waitcnt vmcnt(8)
	s_waitcnt lgkmcnt(0)
	s_setprio 1
	s_barrier
	s_waitcnt lgkmcnt(0)
	v_mfma_f32_16x16x32_bf16 v[124:127], v[128:131], v[190:193], v[124:127]
	v_mfma_f32_16x16x32_bf16 v[120:123], v[136:139], v[190:193], v[120:123]
	v_mfma_f32_16x16x32_bf16 v[108:111], v[128:131], v[214:217], v[108:111]
	v_mfma_f32_16x16x32_bf16 v[104:107], v[136:139], v[214:217], v[104:107]
	v_mfma_f32_16x16x32_bf16 v[92:95], v[128:131], v[224:227], v[92:95]
	v_mfma_f32_16x16x32_bf16 v[88:91], v[136:139], v[224:227], v[88:91]
	v_mfma_f32_16x16x32_bf16 v[76:79], v[128:131], v[232:235], v[76:79]
	v_mfma_f32_16x16x32_bf16 v[72:75], v[136:139], v[232:235], v[72:75]
	v_mfma_f32_16x16x32_bf16 v[124:127], v[132:135], v[194:197], v[124:127]
	v_mfma_f32_16x16x32_bf16 v[120:123], v[140:143], v[194:197], v[120:123]
	v_mfma_f32_16x16x32_bf16 v[108:111], v[132:135], v[218:221], v[108:111]
	v_mfma_f32_16x16x32_bf16 v[104:107], v[140:143], v[218:221], v[104:107]
	v_mfma_f32_16x16x32_bf16 v[92:95], v[132:135], v[228:231], v[92:95]
	v_mfma_f32_16x16x32_bf16 v[88:91], v[140:143], v[228:231], v[88:91]
	v_mfma_f32_16x16x32_bf16 v[76:79], v[132:135], v[236:239], v[76:79]
	v_mfma_f32_16x16x32_bf16 v[72:75], v[140:143], v[236:239], v[72:75]
	s_setprio 0
	s_setprio 1
	v_mfma_f32_16x16x32_bf16 v[116:119], v[144:147], v[190:193], v[116:119]
	v_mfma_f32_16x16x32_bf16 v[112:115], v[182:185], v[190:193], v[112:115]
	v_mfma_f32_16x16x32_bf16 v[100:103], v[144:147], v[214:217], v[100:103]
	v_mfma_f32_16x16x32_bf16 v[96:99], v[182:185], v[214:217], v[96:99]
	v_mfma_f32_16x16x32_bf16 v[84:87], v[144:147], v[224:227], v[84:87]
	v_mfma_f32_16x16x32_bf16 v[80:83], v[182:185], v[224:227], v[80:83]
	v_mfma_f32_16x16x32_bf16 v[68:71], v[144:147], v[232:235], v[68:71]
	v_mfma_f32_16x16x32_bf16 v[64:67], v[182:185], v[232:235], v[64:67]
	v_mfma_f32_16x16x32_bf16 v[116:119], v[148:151], v[194:197], v[116:119]
	v_mfma_f32_16x16x32_bf16 v[112:115], v[186:189], v[194:197], v[112:115]
	v_mfma_f32_16x16x32_bf16 v[100:103], v[148:151], v[218:221], v[100:103]
	v_mfma_f32_16x16x32_bf16 v[96:99], v[186:189], v[218:221], v[96:99]
	v_mfma_f32_16x16x32_bf16 v[84:87], v[148:151], v[228:231], v[84:87]
	v_mfma_f32_16x16x32_bf16 v[80:83], v[186:189], v[228:231], v[80:83]
	v_mfma_f32_16x16x32_bf16 v[68:71], v[148:151], v[236:239], v[68:71]
	v_mfma_f32_16x16x32_bf16 v[64:67], v[186:189], v[236:239], v[64:67]
	s_setprio 0
	s_barrier
	s_add_i32 s60, s87, s68
	v_lshl_add_u64 v[198:199], v[198:199], 0, s[22:23]
	s_mov_b32 m0, s60
	ds_read_b128 v[190:193], v212 offset:49152
	ds_read_b128 v[194:197], v212 offset:50176
	ds_read_b128 v[214:217], v212 offset:51200
	ds_read_b128 v[218:221], v212 offset:52224
	ds_read_b128 v[224:227], v212 offset:53248
	ds_read_b128 v[228:231], v212 offset:54272
	ds_read_b128 v[232:235], v212 offset:55296
	ds_read_b128 v[236:239], v212 offset:56320
	global_load_lds_dwordx4 v[198:199], off
	s_add_i32 m0, s60, 0x2000
	s_add_u32 s18, s18, 0xb0080
	v_lshl_add_u64 v[198:199], v[240:241], 0, s[22:23]
	s_addc_u32 s19, s19, 0
	s_add_i32 s60, s92, s68
	global_load_lds_dwordx4 v[198:199], off
	v_lshl_add_u64 v[198:199], s[18:19], 0, v[152:153]
	s_mov_b32 m0, s60
	s_nop 0
	global_load_lds_dwordx4 v[198:199], off
	v_lshl_add_u64 v[198:199], s[18:19], 0, v[172:173]
	s_add_i32 m0, s60, 0x2000
	s_nop 0
	global_load_lds_dwordx4 v[198:199], off
	v_lshl_add_u64 v[198:199], v[242:243], 0, s[22:23]
	s_mov_b32 m0, s79
	s_nop 0
	global_load_lds_dwordx4 v[198:199], off
	v_lshl_add_u64 v[198:199], v[244:245], 0, s[22:23]
	s_mov_b32 m0, s80
	s_nop 0
	global_load_lds_dwordx4 v[198:199], off
	s_waitcnt vmcnt(8)
	s_waitcnt lgkmcnt(0)
	s_setprio 1
	s_barrier
	s_waitcnt lgkmcnt(0)
	v_mfma_f32_16x16x32_bf16 v[60:63], v[128:131], v[190:193], v[60:63]
	v_mfma_f32_16x16x32_bf16 v[56:59], v[136:139], v[190:193], v[56:59]
	v_mfma_f32_16x16x32_bf16 v[44:47], v[128:131], v[214:217], v[44:47]
	v_mfma_f32_16x16x32_bf16 v[40:43], v[136:139], v[214:217], v[40:43]
	v_mfma_f32_16x16x32_bf16 v[28:31], v[128:131], v[224:227], v[28:31]
	v_mfma_f32_16x16x32_bf16 v[24:27], v[136:139], v[224:227], v[24:27]
	v_mfma_f32_16x16x32_bf16 v[12:15], v[128:131], v[232:235], v[12:15]
	v_mfma_f32_16x16x32_bf16 v[8:11], v[136:139], v[232:235], v[8:11]
	v_mfma_f32_16x16x32_bf16 v[60:63], v[132:135], v[194:197], v[60:63]
	v_mfma_f32_16x16x32_bf16 v[56:59], v[140:143], v[194:197], v[56:59]
	v_mfma_f32_16x16x32_bf16 v[44:47], v[132:135], v[218:221], v[44:47]
	v_mfma_f32_16x16x32_bf16 v[40:43], v[140:143], v[218:221], v[40:43]
	v_mfma_f32_16x16x32_bf16 v[28:31], v[132:135], v[228:231], v[28:31]
	v_mfma_f32_16x16x32_bf16 v[24:27], v[140:143], v[228:231], v[24:27]
	v_mfma_f32_16x16x32_bf16 v[12:15], v[132:135], v[236:239], v[12:15]
	v_mfma_f32_16x16x32_bf16 v[8:11], v[140:143], v[236:239], v[8:11]
	s_setprio 0
	s_setprio 1
	v_mfma_f32_16x16x32_bf16 v[52:55], v[144:147], v[190:193], v[52:55]
	v_mfma_f32_16x16x32_bf16 v[48:51], v[182:185], v[190:193], v[48:51]
	v_mfma_f32_16x16x32_bf16 v[36:39], v[144:147], v[214:217], v[36:39]
	v_mfma_f32_16x16x32_bf16 v[32:35], v[182:185], v[214:217], v[32:35]
	v_mfma_f32_16x16x32_bf16 v[20:23], v[144:147], v[224:227], v[20:23]
	v_mfma_f32_16x16x32_bf16 v[16:19], v[182:185], v[224:227], v[16:19]
	v_mfma_f32_16x16x32_bf16 v[4:7], v[144:147], v[232:235], v[4:7]
	v_mfma_f32_16x16x32_bf16 v[0:3], v[182:185], v[232:235], v[0:3]
	v_mfma_f32_16x16x32_bf16 v[52:55], v[148:151], v[194:197], v[52:55]
	v_mfma_f32_16x16x32_bf16 v[48:51], v[186:189], v[194:197], v[48:51]
	v_mfma_f32_16x16x32_bf16 v[36:39], v[148:151], v[218:221], v[36:39]
	v_mfma_f32_16x16x32_bf16 v[32:35], v[186:189], v[218:221], v[32:35]
	v_mfma_f32_16x16x32_bf16 v[20:23], v[148:151], v[228:231], v[20:23]
	v_mfma_f32_16x16x32_bf16 v[16:19], v[186:189], v[228:231], v[16:19]
	v_mfma_f32_16x16x32_bf16 v[4:7], v[148:151], v[236:239], v[4:7]
	v_mfma_f32_16x16x32_bf16 v[0:3], v[186:189], v[236:239], v[0:3]
	s_setprio 0
	s_barrier
	s_add_i32 s86, s86, 2
	s_add_u32 s84, s84, 0x100
	s_addc_u32 s85, s85, 0
	s_cmp_gt_u32 s86, 41
	s_mov_b64 s[60:61], vcc

.LBB0_284:
	v_lshl_add_u32 v184, s8, 8, v209
	v_lshl_or_b32 v182, s83, 8, v211
	v_ashrrev_i32_e32 v185, 31, v184
	s_andn2_b64 vcc, exec, s[20:21]
	v_ashrrev_i32_e32 v183, 31, v182
	s_cbranch_vccnz .LBB0_303
	v_or_b32_e32 v198, 0, v184
	v_ashrrev_i32_e32 v199, 31, v198
	v_lshlrev_b64 v[198:199], 10, v[198:199]
	v_lshl_add_u64 v[198:199], v[198:199], 0, v[182:183]
	v_lshl_add_u64 v[198:199], v[198:199], 2, s[16:17]
	global_load_dwordx4 v[148:151], v[198:199], off offset:16
	global_load_dwordx4 v[186:189], v[198:199], off
	global_load_dwordx4 v[190:193], v[198:199], off offset:528
	global_load_dwordx4 v[194:197], v[198:199], off offset:512
	v_or_b32_e32 v198, 16, v184
	v_ashrrev_i32_e32 v199, 31, v198
	v_lshlrev_b64 v[198:199], 10, v[198:199]
	v_lshl_add_u64 v[198:199], v[198:199], 0, v[182:183]
	v_lshl_add_u64 v[198:199], v[198:199], 2, s[16:17]
	global_load_dwordx4 v[214:217], v[198:199], off offset:16
	global_load_dwordx4 v[218:221], v[198:199], off
	global_load_dwordx4 v[224:227], v[198:199], off offset:528
	global_load_dwordx4 v[228:231], v[198:199], off offset:512
	v_or_b32_e32 v198, 32, v184
	v_ashrrev_i32_e32 v199, 31, v198
	v_lshlrev_b64 v[198:199], 10, v[198:199]
	v_lshl_add_u64 v[198:199], v[198:199], 0, v[182:183]
	v_lshl_add_u64 v[198:199], v[198:199], 2, s[16:17]
	global_load_dwordx4 v[232:235], v[198:199], off offset:16
	global_load_dwordx4 v[236:239], v[198:199], off
	v_lshlrev_b64 v[128:129], 10, v[184:185]
	v_lshl_add_u64 v[136:137], v[128:129], 0, v[182:183]
	v_lshl_add_u64 v[138:139], v[136:137], 2, s[16:17]
	v_lshl_add_u64 v[136:137], v[136:137], 1, s[26:27]
	s_lshl_b32 s60, s83, 2
	s_ashr_i32 s61, s60, 31
	s_waitcnt vmcnt(6)
	v_pk_fma_f32 v[142:143], v[120:121], 0.5, v[148:149] op_sel_hi:[1,0,1]
	v_pk_fma_f32 v[134:135], v[126:127], 0.5, v[188:189] op_sel_hi:[1,0,1]
	v_pk_fma_f32 v[132:133], v[124:125], 0.5, v[186:187] op_sel_hi:[1,0,1]
	v_pk_fma_f32 v[140:141], v[122:123], 0.5, v[150:151] op_sel_hi:[1,0,1]
	v_cvt_pk_bf16_f32 v128, v132, v133
	v_cvt_pk_bf16_f32 v129, v134, v135
	v_cvt_pk_bf16_f32 v130, v142, v143
	s_nop 0
	v_cvt_pk_bf16_f32 v131, v140, v141
	global_store_dwordx4 v[136:137], v[128:131], off
	s_nop 1
	v_mul_f32_e32 v128, v133, v133
	v_mul_f32_e32 v129, v135, v135
	v_fmac_f32_e32 v128, v132, v132
	v_fmac_f32_e32 v129, v134, v134
	v_add_f32_e32 v128, v128, v129
	v_mul_f32_e32 v129, v143, v143
	v_fmac_f32_e32 v129, v142, v142
	v_add_f32_e32 v128, v129, v128
	v_mul_f32_e32 v129, v141, v141
	v_fmac_f32_e32 v129, v140, v140
	v_add_f32_e32 v142, v129, v128
	v_pk_fma_f32 v[140:141], v[112:113], 0.5, v[190:191] op_sel_hi:[1,0,1]
	v_pk_fma_f32 v[134:135], v[118:119], 0.5, v[196:197] op_sel_hi:[1,0,1]
	v_pk_fma_f32 v[132:133], v[116:117], 0.5, v[194:195] op_sel_hi:[1,0,1]
	v_pk_fma_f32 v[138:139], v[114:115], 0.5, v[192:193] op_sel_hi:[1,0,1]
	v_cvt_pk_bf16_f32 v128, v132, v133
	v_cvt_pk_bf16_f32 v129, v134, v135
	v_cvt_pk_bf16_f32 v130, v140, v141
	s_nop 0
	v_cvt_pk_bf16_f32 v131, v138, v139
	global_store_dwordx4 v[136:137], v[128:131], off offset:256
	s_nop 1
	v_mul_f32_e32 v128, v133, v133
	v_mul_f32_e32 v129, v135, v135
	v_fmac_f32_e32 v128, v132, v132
	v_fmac_f32_e32 v129, v134, v134
	v_add_f32_e32 v128, v128, v129
	v_mul_f32_e32 v129, v141, v141
	v_fmac_f32_e32 v129, v140, v140
	v_add_f32_e32 v128, v129, v128
	v_mul_f32_e32 v129, v139, v139
	v_fmac_f32_e32 v129, v138, v138
	v_add_f32_e32 v128, v129, v128
	v_xor_b32_e32 v129, 16, v204
	v_cmp_lt_i32_e32 vcc, v129, v205
	v_add_f32_e32 v128, v142, v128
	s_nop 0
	v_cndmask_b32_e32 v129, v204, v129, vcc
	v_lshlrev_b32_e32 v130, 2, v129
	ds_bpermute_b32 v129, v130, v128
	s_waitcnt lgkmcnt(0)
	v_add_f32_e32 v128, v128, v129
	v_xor_b32_e32 v129, 32, v204
	v_cmp_lt_i32_e32 vcc, v129, v205
	s_nop 1
	v_cndmask_b32_e32 v129, v204, v129, vcc
	v_lshlrev_b32_e32 v131, 2, v129
	ds_bpermute_b32 v129, v131, v128
	s_and_saveexec_b64 s[18:19], s[46:47]
	s_cbranch_execz .LBB0_287
	v_lshlrev_b64 v[132:133], 6, v[184:185]
	v_lshl_add_u64 v[132:133], s[28:29], 0, v[132:133]
	v_lshl_add_u64 v[132:133], s[60:61], 2, v[132:133]
	s_lshl_b32 s8, s78, 2
	v_lshl_add_u64 v[132:133], v[132:133], 0, s[8:9]
	s_waitcnt lgkmcnt(0)
	v_add_f32_e32 v128, v128, v129
	flat_store_dword v[132:133], v128
.LBB0_287:
	s_or_b64 exec, exec, s[18:19]
	v_or_b32_e32 v198, 32, v184
	v_ashrrev_i32_e32 v199, 31, v198
	v_lshlrev_b64 v[198:199], 10, v[198:199]
	v_lshl_add_u64 v[198:199], v[198:199], 0, v[182:183]
	v_lshl_add_u64 v[198:199], v[198:199], 2, s[16:17]
	global_load_dwordx4 v[112:115], v[198:199], off offset:528
	global_load_dwordx4 v[116:119], v[198:199], off offset:512
	v_or_b32_e32 v198, 48, v184
	v_ashrrev_i32_e32 v199, 31, v198
	v_lshlrev_b64 v[198:199], 10, v[198:199]
	v_lshl_add_u64 v[198:199], v[198:199], 0, v[182:183]
	v_lshl_add_u64 v[198:199], v[198:199], 2, s[16:17]
	global_load_dwordx4 v[120:123], v[198:199], off offset:16
	global_load_dwordx4 v[124:127], v[198:199], off
	global_load_dwordx4 v[148:151], v[198:199], off offset:528
	global_load_dwordx4 v[186:189], v[198:199], off offset:512
	v_add_u32_e32 v198, 128, v184
	v_ashrrev_i32_e32 v199, 31, v198
	v_lshlrev_b64 v[198:199], 10, v[198:199]
	v_lshl_add_u64 v[198:199], v[198:199], 0, v[182:183]
	v_lshl_add_u64 v[198:199], v[198:199], 2, s[16:17]
	global_load_dwordx4 v[190:193], v[198:199], off offset:16
	global_load_dwordx4 v[194:197], v[198:199], off
	v_or_b32_e32 v128, 16, v184
	s_waitcnt lgkmcnt(0)
	v_ashrrev_i32_e32 v129, 31, v128
	v_lshlrev_b64 v[132:133], 10, v[128:129]
	v_lshl_add_u64 v[140:141], v[132:133], 0, v[182:183]
	v_lshl_add_u64 v[142:143], v[140:141], 2, s[16:17]
	v_lshl_add_u64 v[140:141], v[140:141], 1, s[26:27]
	s_waitcnt vmcnt(13)
	v_pk_fma_f32 v[146:147], v[104:105], 0.5, v[214:215] op_sel_hi:[1,0,1]
	v_pk_fma_f32 v[138:139], v[110:111], 0.5, v[220:221] op_sel_hi:[1,0,1]
	v_pk_fma_f32 v[136:137], v[108:109], 0.5, v[218:219] op_sel_hi:[1,0,1]
	v_pk_fma_f32 v[144:145], v[106:107], 0.5, v[216:217] op_sel_hi:[1,0,1]
	v_cvt_pk_bf16_f32 v132, v136, v137
	v_cvt_pk_bf16_f32 v133, v138, v139
	v_cvt_pk_bf16_f32 v134, v146, v147
	s_nop 0
	v_cvt_pk_bf16_f32 v135, v144, v145
	global_store_dwordx4 v[140:141], v[132:135], off
	s_nop 1
	v_mul_f32_e32 v132, v137, v137
	v_mul_f32_e32 v133, v139, v139
	v_fmac_f32_e32 v132, v136, v136
	v_fmac_f32_e32 v133, v138, v138
	v_add_f32_e32 v132, v132, v133
	v_mul_f32_e32 v133, v147, v147
	v_fmac_f32_e32 v133, v146, v146
	v_add_f32_e32 v132, v133, v132
	v_mul_f32_e32 v133, v145, v145
	v_fmac_f32_e32 v133, v144, v144
	v_add_f32_e32 v146, v133, v132
	v_pk_fma_f32 v[144:145], v[96:97], 0.5, v[224:225] op_sel_hi:[1,0,1]
	v_pk_fma_f32 v[138:139], v[102:103], 0.5, v[230:231] op_sel_hi:[1,0,1]
	v_pk_fma_f32 v[136:137], v[100:101], 0.5, v[228:229] op_sel_hi:[1,0,1]
	v_pk_fma_f32 v[142:143], v[98:99], 0.5, v[226:227] op_sel_hi:[1,0,1]
	v_cvt_pk_bf16_f32 v132, v136, v137
	v_cvt_pk_bf16_f32 v133, v138, v139
	v_cvt_pk_bf16_f32 v134, v144, v145
	s_nop 0
	v_cvt_pk_bf16_f32 v135, v142, v143
	global_store_dwordx4 v[140:141], v[132:135], off offset:256
	s_nop 1
	v_mul_f32_e32 v132, v137, v137
	v_mul_f32_e32 v133, v139, v139
	v_fmac_f32_e32 v132, v136, v136
	v_fmac_f32_e32 v133, v138, v138
	v_add_f32_e32 v132, v132, v133
	v_mul_f32_e32 v133, v145, v145
	v_fmac_f32_e32 v133, v144, v144
	v_add_f32_e32 v132, v133, v132
	v_mul_f32_e32 v133, v143, v143
	v_fmac_f32_e32 v133, v142, v142
	v_add_f32_e32 v132, v133, v132
	v_add_f32_e32 v132, v146, v132
	ds_bpermute_b32 v133, v130, v132
	s_waitcnt lgkmcnt(0)
	v_add_f32_e32 v132, v132, v133
	ds_bpermute_b32 v133, v131, v132
	s_and_saveexec_b64 s[18:19], s[46:47]
	s_cbranch_execz .LBB0_289
	v_lshlrev_b64 v[128:129], 6, v[128:129]
	v_lshl_add_u64 v[128:129], s[28:29], 0, v[128:129]
	v_lshl_add_u64 v[128:129], s[60:61], 2, v[128:129]
	s_lshl_b32 s8, s78, 2
	v_lshl_add_u64 v[128:129], v[128:129], 0, s[8:9]
	s_waitcnt lgkmcnt(0)
	v_add_f32_e32 v132, v132, v133
	flat_store_dword v[128:129], v132
.LBB0_289:
	s_or_b64 exec, exec, s[18:19]
	v_add_u32_e32 v198, 128, v184
	v_ashrrev_i32_e32 v199, 31, v198
	v_lshlrev_b64 v[198:199], 10, v[198:199]
	v_lshl_add_u64 v[198:199], v[198:199], 0, v[182:183]
	v_lshl_add_u64 v[198:199], v[198:199], 2, s[16:17]
	global_load_dwordx4 v[96:99], v[198:199], off offset:528
	global_load_dwordx4 v[100:103], v[198:199], off offset:512
	v_add_u32_e32 v198, 144, v184
	v_ashrrev_i32_e32 v199, 31, v198
	v_lshlrev_b64 v[198:199], 10, v[198:199]
	v_lshl_add_u64 v[198:199], v[198:199], 0, v[182:183]
	v_lshl_add_u64 v[198:199], v[198:199], 2, s[16:17]
	global_load_dwordx4 v[104:107], v[198:199], off offset:16
	global_load_dwordx4 v[108:111], v[198:199], off
	global_load_dwordx4 v[214:217], v[198:199], off offset:528
	global_load_dwordx4 v[218:221], v[198:199], off offset:512
	v_add_u32_e32 v198, 160, v184
	v_ashrrev_i32_e32 v199, 31, v198
	v_lshlrev_b64 v[198:199], 10, v[198:199]
	v_lshl_add_u64 v[198:199], v[198:199], 0, v[182:183]
	v_lshl_add_u64 v[198:199], v[198:199], 2, s[16:17]
	global_load_dwordx4 v[224:227], v[198:199], off offset:16
	global_load_dwordx4 v[228:231], v[198:199], off
	v_or_b32_e32 v128, 32, v184
	v_ashrrev_i32_e32 v129, 31, v128
	s_waitcnt lgkmcnt(0)
	v_lshlrev_b64 v[132:133], 10, v[128:129]
	v_lshl_add_u64 v[140:141], v[132:133], 0, v[182:183]
	v_lshl_add_u64 v[142:143], v[140:141], 2, s[16:17]
	v_lshl_add_u64 v[140:141], v[140:141], 1, s[26:27]
	s_waitcnt vmcnt(17)
	v_pk_fma_f32 v[146:147], v[88:89], 0.5, v[232:233] op_sel_hi:[1,0,1]
	v_pk_fma_f32 v[138:139], v[94:95], 0.5, v[238:239] op_sel_hi:[1,0,1]
	v_pk_fma_f32 v[136:137], v[92:93], 0.5, v[236:237] op_sel_hi:[1,0,1]
	v_pk_fma_f32 v[144:145], v[90:91], 0.5, v[234:235] op_sel_hi:[1,0,1]
	v_cvt_pk_bf16_f32 v132, v136, v137
	v_cvt_pk_bf16_f32 v133, v138, v139
	v_cvt_pk_bf16_f32 v134, v146, v147
	s_nop 0
	v_cvt_pk_bf16_f32 v135, v144, v145
	global_store_dwordx4 v[140:141], v[132:135], off
	s_nop 1
	v_mul_f32_e32 v132, v137, v137
	v_mul_f32_e32 v133, v139, v139
	v_fmac_f32_e32 v132, v136, v136
	v_fmac_f32_e32 v133, v138, v138
	v_add_f32_e32 v132, v132, v133
	v_mul_f32_e32 v133, v147, v147
	v_fmac_f32_e32 v133, v146, v146
	v_add_f32_e32 v132, v133, v132
	v_mul_f32_e32 v133, v145, v145
	v_fmac_f32_e32 v133, v144, v144
	v_add_f32_e32 v146, v133, v132
	v_pk_fma_f32 v[144:145], v[80:81], 0.5, v[112:113] op_sel_hi:[1,0,1]
	v_pk_fma_f32 v[138:139], v[86:87], 0.5, v[118:119] op_sel_hi:[1,0,1]
	v_pk_fma_f32 v[136:137], v[84:85], 0.5, v[116:117] op_sel_hi:[1,0,1]
	v_pk_fma_f32 v[142:143], v[82:83], 0.5, v[114:115] op_sel_hi:[1,0,1]
	v_cvt_pk_bf16_f32 v132, v136, v137
	v_cvt_pk_bf16_f32 v133, v138, v139
	v_cvt_pk_bf16_f32 v134, v144, v145
	s_nop 0
	v_cvt_pk_bf16_f32 v135, v142, v143
	global_store_dwordx4 v[140:141], v[132:135], off offset:256
	s_nop 1
	v_mul_f32_e32 v132, v137, v137
	v_mul_f32_e32 v133, v139, v139
	v_fmac_f32_e32 v132, v136, v136
	v_fmac_f32_e32 v133, v138, v138
	v_add_f32_e32 v132, v132, v133
	v_mul_f32_e32 v133, v145, v145
	v_fmac_f32_e32 v133, v144, v144
	v_add_f32_e32 v132, v133, v132
	v_mul_f32_e32 v133, v143, v143
	v_fmac_f32_e32 v133, v142, v142
	v_add_f32_e32 v132, v133, v132
	v_add_f32_e32 v132, v146, v132
	ds_bpermute_b32 v133, v130, v132
	s_waitcnt lgkmcnt(0)
	v_add_f32_e32 v132, v132, v133
	ds_bpermute_b32 v133, v131, v132
	s_and_saveexec_b64 s[18:19], s[46:47]
	s_cbranch_execz .LBB0_291
	v_lshlrev_b64 v[128:129], 6, v[128:129]
	v_lshl_add_u64 v[128:129], s[28:29], 0, v[128:129]
	v_lshl_add_u64 v[128:129], s[60:61], 2, v[128:129]
	s_lshl_b32 s8, s78, 2
	v_lshl_add_u64 v[128:129], v[128:129], 0, s[8:9]
	s_waitcnt lgkmcnt(0)
	v_add_f32_e32 v132, v132, v133
	flat_store_dword v[128:129], v132
.LBB0_291:
	s_or_b64 exec, exec, s[18:19]
	v_add_u32_e32 v198, 160, v184
	v_ashrrev_i32_e32 v199, 31, v198
	v_lshlrev_b64 v[198:199], 10, v[198:199]
	v_lshl_add_u64 v[198:199], v[198:199], 0, v[182:183]
	v_lshl_add_u64 v[198:199], v[198:199], 2, s[16:17]
	global_load_dwordx4 v[80:83], v[198:199], off offset:528
	global_load_dwordx4 v[84:87], v[198:199], off offset:512
	v_add_u32_e32 v198, 176, v184
	v_ashrrev_i32_e32 v199, 31, v198
	v_lshlrev_b64 v[198:199], 10, v[198:199]
	v_lshl_add_u64 v[198:199], v[198:199], 0, v[182:183]
	v_lshl_add_u64 v[198:199], v[198:199], 2, s[16:17]
	global_load_dwordx4 v[88:91], v[198:199], off offset:16
	global_load_dwordx4 v[92:95], v[198:199], off
	global_load_dwordx4 v[232:235], v[198:199], off offset:528
	global_load_dwordx4 v[236:239], v[198:199], off offset:512
	v_or_b32_e32 v128, 48, v184
	v_ashrrev_i32_e32 v129, 31, v128
	s_waitcnt lgkmcnt(0)
	v_lshlrev_b64 v[132:133], 10, v[128:129]
	v_lshl_add_u64 v[140:141], v[132:133], 0, v[182:183]
	v_lshl_add_u64 v[142:143], v[140:141], 2, s[16:17]
	v_lshl_add_u64 v[140:141], v[140:141], 1, s[26:27]
	s_waitcnt vmcnt(22)
	v_pk_fma_f32 v[146:147], v[72:73], 0.5, v[120:121] op_sel_hi:[1,0,1]
	v_pk_fma_f32 v[138:139], v[78:79], 0.5, v[126:127] op_sel_hi:[1,0,1]
	v_pk_fma_f32 v[136:137], v[76:77], 0.5, v[124:125] op_sel_hi:[1,0,1]
	v_pk_fma_f32 v[144:145], v[74:75], 0.5, v[122:123] op_sel_hi:[1,0,1]
	v_cvt_pk_bf16_f32 v132, v136, v137
	v_cvt_pk_bf16_f32 v133, v138, v139
	v_cvt_pk_bf16_f32 v134, v146, v147
	s_nop 0
	v_cvt_pk_bf16_f32 v135, v144, v145
	global_store_dwordx4 v[140:141], v[132:135], off
	s_nop 1
	v_mul_f32_e32 v132, v137, v137
	v_mul_f32_e32 v133, v139, v139
	v_fmac_f32_e32 v132, v136, v136
	v_fmac_f32_e32 v133, v138, v138
	v_add_f32_e32 v132, v132, v133
	v_mul_f32_e32 v133, v147, v147
	v_fmac_f32_e32 v133, v146, v146
	v_add_f32_e32 v132, v133, v132
	v_mul_f32_e32 v133, v145, v145
	v_fmac_f32_e32 v133, v144, v144
	v_add_f32_e32 v146, v133, v132
	v_pk_fma_f32 v[144:145], v[64:65], 0.5, v[148:149] op_sel_hi:[1,0,1]
	v_pk_fma_f32 v[138:139], v[70:71], 0.5, v[188:189] op_sel_hi:[1,0,1]
	v_pk_fma_f32 v[136:137], v[68:69], 0.5, v[186:187] op_sel_hi:[1,0,1]
	v_pk_fma_f32 v[142:143], v[66:67], 0.5, v[150:151] op_sel_hi:[1,0,1]
	v_cvt_pk_bf16_f32 v132, v136, v137
	v_cvt_pk_bf16_f32 v133, v138, v139
	v_cvt_pk_bf16_f32 v134, v144, v145
	s_nop 0
	v_cvt_pk_bf16_f32 v135, v142, v143
	global_store_dwordx4 v[140:141], v[132:135], off offset:256
	s_nop 1
	v_mul_f32_e32 v132, v137, v137
	v_mul_f32_e32 v133, v139, v139
	v_fmac_f32_e32 v132, v136, v136
	v_fmac_f32_e32 v133, v138, v138
	v_add_f32_e32 v132, v132, v133
	v_mul_f32_e32 v133, v145, v145
	v_fmac_f32_e32 v133, v144, v144
	v_add_f32_e32 v132, v133, v132
	v_mul_f32_e32 v133, v143, v143
	v_fmac_f32_e32 v133, v142, v142
	v_add_f32_e32 v132, v133, v132
	v_add_f32_e32 v132, v146, v132
	ds_bpermute_b32 v133, v130, v132
	s_waitcnt lgkmcnt(0)
	v_add_f32_e32 v132, v132, v133
	ds_bpermute_b32 v133, v131, v132
	s_and_saveexec_b64 s[18:19], s[46:47]
	s_cbranch_execz .LBB0_293
	v_lshlrev_b64 v[128:129], 6, v[128:129]
	v_lshl_add_u64 v[128:129], s[28:29], 0, v[128:129]
	v_lshl_add_u64 v[128:129], s[60:61], 2, v[128:129]
	s_lshl_b32 s8, s78, 2
	v_lshl_add_u64 v[128:129], v[128:129], 0, s[8:9]
	s_waitcnt lgkmcnt(0)
	v_add_f32_e32 v132, v132, v133
	flat_store_dword v[128:129], v132
.LBB0_293:
	s_or_b64 exec, exec, s[18:19]
	v_add_u32_e32 v128, 0x80, v184
	v_ashrrev_i32_e32 v129, 31, v128
	s_waitcnt lgkmcnt(0)
	v_lshlrev_b64 v[132:133], 10, v[128:129]
	v_lshl_add_u64 v[140:141], v[132:133], 0, v[182:183]
	v_lshl_add_u64 v[142:143], v[140:141], 2, s[16:17]
	v_lshl_add_u64 v[140:141], v[140:141], 1, s[26:27]
	s_waitcnt vmcnt(18)
	v_pk_fma_f32 v[146:147], v[56:57], 0.5, v[190:191] op_sel_hi:[1,0,1]
	v_pk_fma_f32 v[138:139], v[62:63], 0.5, v[196:197] op_sel_hi:[1,0,1]
	v_pk_fma_f32 v[136:137], v[60:61], 0.5, v[194:195] op_sel_hi:[1,0,1]
	v_pk_fma_f32 v[144:145], v[58:59], 0.5, v[192:193] op_sel_hi:[1,0,1]
	v_cvt_pk_bf16_f32 v132, v136, v137
	v_cvt_pk_bf16_f32 v133, v138, v139
	v_cvt_pk_bf16_f32 v134, v146, v147
	s_nop 0
	v_cvt_pk_bf16_f32 v135, v144, v145
	global_store_dwordx4 v[140:141], v[132:135], off
	s_nop 1
	v_mul_f32_e32 v132, v137, v137
	v_mul_f32_e32 v133, v139, v139
	v_fmac_f32_e32 v132, v136, v136
	v_fmac_f32_e32 v133, v138, v138
	v_add_f32_e32 v132, v132, v133
	v_mul_f32_e32 v133, v147, v147
	v_fmac_f32_e32 v133, v146, v146
	v_add_f32_e32 v132, v133, v132
	v_mul_f32_e32 v133, v145, v145
	v_fmac_f32_e32 v133, v144, v144
	v_add_f32_e32 v146, v133, v132
	v_pk_fma_f32 v[144:145], v[48:49], 0.5, v[96:97] op_sel_hi:[1,0,1]
	v_pk_fma_f32 v[138:139], v[54:55], 0.5, v[102:103] op_sel_hi:[1,0,1]
	v_pk_fma_f32 v[136:137], v[52:53], 0.5, v[100:101] op_sel_hi:[1,0,1]
	v_pk_fma_f32 v[142:143], v[50:51], 0.5, v[98:99] op_sel_hi:[1,0,1]
	v_cvt_pk_bf16_f32 v132, v136, v137
	v_cvt_pk_bf16_f32 v133, v138, v139
	v_cvt_pk_bf16_f32 v134, v144, v145
	s_nop 0
	v_cvt_pk_bf16_f32 v135, v142, v143
	global_store_dwordx4 v[140:141], v[132:135], off offset:256
	s_nop 1
	v_mul_f32_e32 v132, v137, v137
	v_mul_f32_e32 v133, v139, v139
	v_fmac_f32_e32 v132, v136, v136
	v_fmac_f32_e32 v133, v138, v138
	v_add_f32_e32 v132, v132, v133
	v_mul_f32_e32 v133, v145, v145
	v_fmac_f32_e32 v133, v144, v144
	v_add_f32_e32 v132, v133, v132
	v_mul_f32_e32 v133, v143, v143
	v_fmac_f32_e32 v133, v142, v142
	v_add_f32_e32 v132, v133, v132
	v_add_f32_e32 v132, v146, v132
	ds_bpermute_b32 v133, v130, v132
	s_waitcnt lgkmcnt(0)
	v_add_f32_e32 v132, v132, v133
	ds_bpermute_b32 v133, v131, v132
	s_and_saveexec_b64 s[18:19], s[46:47]
	s_cbranch_execz .LBB0_295
	v_lshlrev_b64 v[128:129], 6, v[128:129]
	v_lshl_add_u64 v[128:129], s[28:29], 0, v[128:129]
	v_lshl_add_u64 v[128:129], s[60:61], 2, v[128:129]
	s_lshl_b32 s8, s78, 2
	v_lshl_add_u64 v[128:129], v[128:129], 0, s[8:9]
	s_waitcnt lgkmcnt(0)
	v_add_f32_e32 v132, v132, v133
	flat_store_dword v[128:129], v132
.LBB0_295:
	s_or_b64 exec, exec, s[18:19]
	v_add_u32_e32 v128, 0x90, v184
	v_ashrrev_i32_e32 v129, 31, v128
	s_waitcnt lgkmcnt(0)
	v_lshlrev_b64 v[132:133], 10, v[128:129]
	v_lshl_add_u64 v[140:141], v[132:133], 0, v[182:183]
	v_lshl_add_u64 v[142:143], v[140:141], 2, s[16:17]
	v_lshl_add_u64 v[140:141], v[140:141], 1, s[26:27]
	s_waitcnt vmcnt(17)
	v_pk_fma_f32 v[146:147], v[40:41], 0.5, v[104:105] op_sel_hi:[1,0,1]
	v_pk_fma_f32 v[138:139], v[46:47], 0.5, v[110:111] op_sel_hi:[1,0,1]
	v_pk_fma_f32 v[136:137], v[44:45], 0.5, v[108:109] op_sel_hi:[1,0,1]
	v_pk_fma_f32 v[144:145], v[42:43], 0.5, v[106:107] op_sel_hi:[1,0,1]
	v_cvt_pk_bf16_f32 v132, v136, v137
	v_cvt_pk_bf16_f32 v133, v138, v139
	v_cvt_pk_bf16_f32 v134, v146, v147
	s_nop 0
	v_cvt_pk_bf16_f32 v135, v144, v145
	global_store_dwordx4 v[140:141], v[132:135], off
	s_nop 1
	v_mul_f32_e32 v132, v137, v137
	v_mul_f32_e32 v133, v139, v139
	v_fmac_f32_e32 v132, v136, v136
	v_fmac_f32_e32 v133, v138, v138
	v_add_f32_e32 v132, v132, v133
	v_mul_f32_e32 v133, v147, v147
	v_fmac_f32_e32 v133, v146, v146
	v_add_f32_e32 v132, v133, v132
	v_mul_f32_e32 v133, v145, v145
	v_fmac_f32_e32 v133, v144, v144
	v_add_f32_e32 v146, v133, v132
	v_pk_fma_f32 v[144:145], v[32:33], 0.5, v[214:215] op_sel_hi:[1,0,1]
	v_pk_fma_f32 v[138:139], v[38:39], 0.5, v[220:221] op_sel_hi:[1,0,1]
	v_pk_fma_f32 v[136:137], v[36:37], 0.5, v[218:219] op_sel_hi:[1,0,1]
	v_pk_fma_f32 v[142:143], v[34:35], 0.5, v[216:217] op_sel_hi:[1,0,1]
	v_cvt_pk_bf16_f32 v132, v136, v137
	v_cvt_pk_bf16_f32 v133, v138, v139
	v_cvt_pk_bf16_f32 v134, v144, v145
	s_nop 0
	v_cvt_pk_bf16_f32 v135, v142, v143
	global_store_dwordx4 v[140:141], v[132:135], off offset:256
	s_nop 1
	v_mul_f32_e32 v132, v137, v137
	v_mul_f32_e32 v133, v139, v139
	v_fmac_f32_e32 v132, v136, v136
	v_fmac_f32_e32 v133, v138, v138
	v_add_f32_e32 v132, v132, v133
	v_mul_f32_e32 v133, v145, v145
	v_fmac_f32_e32 v133, v144, v144
	v_add_f32_e32 v132, v133, v132
	v_mul_f32_e32 v133, v143, v143
	v_fmac_f32_e32 v133, v142, v142
	v_add_f32_e32 v132, v133, v132
	v_add_f32_e32 v132, v146, v132
	ds_bpermute_b32 v133, v130, v132
	s_waitcnt lgkmcnt(0)
	v_add_f32_e32 v132, v132, v133
	ds_bpermute_b32 v133, v131, v132
	s_and_saveexec_b64 s[18:19], s[46:47]
	s_cbranch_execz .LBB0_297
	v_lshlrev_b64 v[128:129], 6, v[128:129]
	v_lshl_add_u64 v[128:129], s[28:29], 0, v[128:129]
	v_lshl_add_u64 v[128:129], s[60:61], 2, v[128:129]
	s_lshl_b32 s8, s78, 2
	v_lshl_add_u64 v[128:129], v[128:129], 0, s[8:9]
	s_waitcnt lgkmcnt(0)
	v_add_f32_e32 v132, v132, v133
	flat_store_dword v[128:129], v132
.LBB0_297:
	s_or_b64 exec, exec, s[18:19]
	v_add_u32_e32 v128, 0xa0, v184
	v_ashrrev_i32_e32 v129, 31, v128
	s_waitcnt lgkmcnt(0)
	v_lshlrev_b64 v[132:133], 10, v[128:129]
	v_lshl_add_u64 v[140:141], v[132:133], 0, v[182:183]
	v_lshl_add_u64 v[142:143], v[140:141], 2, s[16:17]
	v_lshl_add_u64 v[140:141], v[140:141], 1, s[26:27]
	s_waitcnt vmcnt(13)
	v_pk_fma_f32 v[146:147], v[24:25], 0.5, v[224:225] op_sel_hi:[1,0,1]
	v_pk_fma_f32 v[138:139], v[30:31], 0.5, v[230:231] op_sel_hi:[1,0,1]
	v_pk_fma_f32 v[136:137], v[28:29], 0.5, v[228:229] op_sel_hi:[1,0,1]
	v_pk_fma_f32 v[144:145], v[26:27], 0.5, v[226:227] op_sel_hi:[1,0,1]
	v_cvt_pk_bf16_f32 v132, v136, v137
	v_cvt_pk_bf16_f32 v133, v138, v139
	v_cvt_pk_bf16_f32 v134, v146, v147
	s_nop 0
	v_cvt_pk_bf16_f32 v135, v144, v145
	global_store_dwordx4 v[140:141], v[132:135], off
	s_nop 1
	v_mul_f32_e32 v132, v137, v137
	v_mul_f32_e32 v133, v139, v139
	v_fmac_f32_e32 v132, v136, v136
	v_fmac_f32_e32 v133, v138, v138
	v_add_f32_e32 v132, v132, v133
	v_mul_f32_e32 v133, v147, v147
	v_fmac_f32_e32 v133, v146, v146
	v_add_f32_e32 v132, v133, v132
	v_mul_f32_e32 v133, v145, v145
	v_fmac_f32_e32 v133, v144, v144
	v_add_f32_e32 v146, v133, v132
	v_pk_fma_f32 v[144:145], v[16:17], 0.5, v[80:81] op_sel_hi:[1,0,1]
	v_pk_fma_f32 v[138:139], v[22:23], 0.5, v[86:87] op_sel_hi:[1,0,1]
	v_pk_fma_f32 v[136:137], v[20:21], 0.5, v[84:85] op_sel_hi:[1,0,1]
	v_pk_fma_f32 v[142:143], v[18:19], 0.5, v[82:83] op_sel_hi:[1,0,1]
	v_cvt_pk_bf16_f32 v132, v136, v137
	v_cvt_pk_bf16_f32 v133, v138, v139
	v_cvt_pk_bf16_f32 v134, v144, v145
	s_nop 0
	v_cvt_pk_bf16_f32 v135, v142, v143
	global_store_dwordx4 v[140:141], v[132:135], off offset:256
	s_nop 1
	v_mul_f32_e32 v132, v137, v137
	v_mul_f32_e32 v133, v139, v139
	v_fmac_f32_e32 v132, v136, v136
	v_fmac_f32_e32 v133, v138, v138
	v_add_f32_e32 v132, v132, v133
	v_mul_f32_e32 v133, v145, v145
	v_fmac_f32_e32 v133, v144, v144
	v_add_f32_e32 v132, v133, v132
	v_mul_f32_e32 v133, v143, v143
	v_fmac_f32_e32 v133, v142, v142
	v_add_f32_e32 v132, v133, v132
	v_add_f32_e32 v132, v146, v132
	ds_bpermute_b32 v133, v130, v132
	s_waitcnt lgkmcnt(0)
	v_add_f32_e32 v132, v132, v133
	ds_bpermute_b32 v133, v131, v132
	s_and_saveexec_b64 s[18:19], s[46:47]
	s_cbranch_execz .LBB0_299
	v_lshlrev_b64 v[128:129], 6, v[128:129]
	v_lshl_add_u64 v[128:129], s[28:29], 0, v[128:129]
	v_lshl_add_u64 v[128:129], s[60:61], 2, v[128:129]
	s_lshl_b32 s8, s78, 2
	v_lshl_add_u64 v[128:129], v[128:129], 0, s[8:9]
	s_waitcnt lgkmcnt(0)
	v_add_f32_e32 v132, v132, v133
	flat_store_dword v[128:129], v132
.LBB0_299:
	s_or_b64 exec, exec, s[18:19]
	v_add_u32_e32 v128, 0xb0, v184
	v_ashrrev_i32_e32 v129, 31, v128
	s_waitcnt lgkmcnt(0)
	v_lshlrev_b64 v[132:133], 10, v[128:129]
	v_lshl_add_u64 v[140:141], v[132:133], 0, v[182:183]
	v_lshl_add_u64 v[142:143], v[140:141], 2, s[16:17]
	v_lshl_add_u64 v[140:141], v[140:141], 1, s[26:27]
	s_waitcnt vmcnt(12)
	v_pk_fma_f32 v[146:147], v[8:9], 0.5, v[88:89] op_sel_hi:[1,0,1]
	v_pk_fma_f32 v[138:139], v[14:15], 0.5, v[94:95] op_sel_hi:[1,0,1]
	v_pk_fma_f32 v[136:137], v[12:13], 0.5, v[92:93] op_sel_hi:[1,0,1]
	v_pk_fma_f32 v[144:145], v[10:11], 0.5, v[90:91] op_sel_hi:[1,0,1]
	v_cvt_pk_bf16_f32 v132, v136, v137
	v_cvt_pk_bf16_f32 v133, v138, v139
	v_cvt_pk_bf16_f32 v134, v146, v147
	s_nop 0
	v_cvt_pk_bf16_f32 v135, v144, v145
	global_store_dwordx4 v[140:141], v[132:135], off
	s_nop 1
	v_mul_f32_e32 v132, v137, v137
	v_mul_f32_e32 v133, v139, v139
	v_fmac_f32_e32 v132, v136, v136
	v_fmac_f32_e32 v133, v138, v138
	v_add_f32_e32 v132, v132, v133
	v_mul_f32_e32 v133, v147, v147
	v_fmac_f32_e32 v133, v146, v146
	v_add_f32_e32 v132, v133, v132
	v_mul_f32_e32 v133, v145, v145
	v_fmac_f32_e32 v133, v144, v144
	v_add_f32_e32 v146, v133, v132
	v_pk_fma_f32 v[144:145], v[0:1], 0.5, v[232:233] op_sel_hi:[1,0,1]
	v_pk_fma_f32 v[138:139], v[6:7], 0.5, v[238:239] op_sel_hi:[1,0,1]
	v_pk_fma_f32 v[136:137], v[4:5], 0.5, v[236:237] op_sel_hi:[1,0,1]
	v_pk_fma_f32 v[142:143], v[2:3], 0.5, v[234:235] op_sel_hi:[1,0,1]
	v_cvt_pk_bf16_f32 v132, v136, v137
	v_cvt_pk_bf16_f32 v133, v138, v139
	v_cvt_pk_bf16_f32 v134, v144, v145
	s_nop 0
	v_cvt_pk_bf16_f32 v135, v142, v143
	global_store_dwordx4 v[140:141], v[132:135], off offset:256
	s_nop 1
	v_mul_f32_e32 v132, v137, v137
	v_mul_f32_e32 v133, v139, v139
	v_fmac_f32_e32 v132, v136, v136
	v_fmac_f32_e32 v133, v138, v138
	v_add_f32_e32 v132, v132, v133
	v_mul_f32_e32 v133, v145, v145
	v_fmac_f32_e32 v133, v144, v144
	v_add_f32_e32 v132, v133, v132
	v_mul_f32_e32 v133, v143, v143
	v_fmac_f32_e32 v133, v142, v142
	v_add_f32_e32 v132, v133, v132
	v_add_f32_e32 v132, v146, v132
	ds_bpermute_b32 v130, v130, v132
	s_waitcnt lgkmcnt(0)
	v_add_f32_e32 v130, v132, v130
	ds_bpermute_b32 v131, v131, v130
	s_and_saveexec_b64 s[18:19], s[46:47]
	s_cbranch_execz .LBB0_301
	v_lshlrev_b64 v[128:129], 6, v[128:129]
	v_lshl_add_u64 v[128:129], s[28:29], 0, v[128:129]
	v_lshl_add_u64 v[128:129], s[60:61], 2, v[128:129]
	s_lshl_b32 s8, s78, 2
	v_lshl_add_u64 v[128:129], v[128:129], 0, s[8:9]
	s_waitcnt lgkmcnt(0)
	v_add_f32_e32 v130, v130, v131
	flat_store_dword v[128:129], v130

.LBB0_418:
	s_ashr_i32 s21, s20, 31
	s_lshl_b64 s[50:51], s[20:21], 19
	s_add_u32 s50, s26, s50
	s_addc_u32 s51, s27, s51
	s_and_b64 s[60:61], s[46:47], exec
	s_cselect_b32 s21, s51, s45
	s_cselect_b32 s78, s50, s44
	s_ashr_i32 s19, s18, 31
	s_lshl_b64 s[60:61], s[18:19], 19
	v_readlane_b32 s19, v254, 42
	s_add_u32 s60, s19, s60
	v_readlane_b32 s19, v254, 43
	s_addc_u32 s61, s19, s61
	s_and_b64 s[62:63], s[46:47], exec
	s_cselect_b32 s19, s61, s49
	s_cselect_b32 s79, s60, s48
	s_add_u32 s80, s48, 0x100
	s_addc_u32 s81, s49, 0
	s_add_u32 s48, s44, 0x40080
	s_addc_u32 s49, s45, 0
	s_mov_b32 s82, -2
	s_add_u32 s44, s48, 0xfffc0080
	s_addc_u32 s45, s49, -1
	s_add_i32 s83, 0, 0x10000
	s_cmp_eq_u32 s82, 12
	s_cselect_b32 s63, s21, s45
	s_cselect_b32 s62, s78, s44
	s_cselect_b32 s45, s19, s81
	s_cselect_b32 s44, s79, s80
	s_add_i32 s86, 0, 0x14000
	v_add_u32_e32 v88, s83, v185
	v_add_u32_e32 v182, s86, v185
	ds_read_b128 v[72:75], v88
	ds_read_b128 v[76:79], v88 offset:1024
	ds_read_b128 v[80:83], v88 offset:2048
	ds_read_b128 v[88:91], v88 offset:3072
	ds_read_b128 v[174:177], v182
	ds_read_b128 v[178:181], v182 offset:1024
	ds_read_b128 v[190:193], v182 offset:2048
	ds_read_b128 v[194:197], v182 offset:3072
	v_lshl_add_u64 v[182:183], s[48:49], 0, v[172:173]
	s_add_i32 m0, s59, 0xc000
	ds_read_b128 v[210:213], v188
	ds_read_b128 v[214:217], v188 offset:1024
	ds_read_b128 v[218:221], v188 offset:2048
	ds_read_b128 v[224:227], v188 offset:3072
	ds_read_b128 v[228:231], v188 offset:4096
	ds_read_b128 v[232:235], v188 offset:5120
	ds_read_b128 v[236:239], v188 offset:6144
	ds_read_b128 v[240:243], v188 offset:7168
	global_load_lds_dwordx4 v[182:183], off
	v_lshl_add_u64 v[182:183], s[48:49], 0, v[150:151]
	s_add_i32 m0, s59, 0xe000
	s_nop 0
	global_load_lds_dwordx4 v[182:183], off
	s_waitcnt vmcnt(8)
	s_waitcnt lgkmcnt(0)
	s_setprio 1
	s_barrier
	s_waitcnt lgkmcnt(0)
	v_mfma_f32_16x16x32_bf16 v[140:143], v[72:75], v[210:213], 0
	v_mfma_f32_16x16x32_bf16 v[136:139], v[80:83], v[210:213], 0
	v_mfma_f32_16x16x32_bf16 v[124:127], v[72:75], v[218:221], 0
	v_mfma_f32_16x16x32_bf16 v[120:123], v[80:83], v[218:221], 0
	v_mfma_f32_16x16x32_bf16 v[108:111], v[72:75], v[228:231], 0
	v_mfma_f32_16x16x32_bf16 v[104:107], v[80:83], v[228:231], 0
	v_mfma_f32_16x16x32_bf16 v[92:95], v[72:75], v[236:239], 0
	v_mfma_f32_16x16x32_bf16 v[84:87], v[80:83], v[236:239], 0
	v_mfma_f32_16x16x32_bf16 v[140:143], v[76:79], v[214:217], v[140:143]
	v_mfma_f32_16x16x32_bf16 v[136:139], v[88:91], v[214:217], v[136:139]
	v_mfma_f32_16x16x32_bf16 v[124:127], v[76:79], v[224:227], v[124:127]
	v_mfma_f32_16x16x32_bf16 v[120:123], v[88:91], v[224:227], v[120:123]
	v_mfma_f32_16x16x32_bf16 v[108:111], v[76:79], v[232:235], v[108:111]
	v_mfma_f32_16x16x32_bf16 v[104:107], v[88:91], v[232:235], v[104:107]
	v_mfma_f32_16x16x32_bf16 v[92:95], v[76:79], v[240:243], v[92:95]
	v_mfma_f32_16x16x32_bf16 v[84:87], v[88:91], v[240:243], v[84:87]
	s_setprio 0
	s_setprio 1
	v_mfma_f32_16x16x32_bf16 v[132:135], v[174:177], v[210:213], 0
	v_mfma_f32_16x16x32_bf16 v[128:131], v[190:193], v[210:213], 0
	v_mfma_f32_16x16x32_bf16 v[116:119], v[174:177], v[218:221], 0
	v_mfma_f32_16x16x32_bf16 v[112:115], v[190:193], v[218:221], 0
	v_mfma_f32_16x16x32_bf16 v[100:103], v[174:177], v[228:231], 0
	v_mfma_f32_16x16x32_bf16 v[96:99], v[190:193], v[228:231], 0
	v_mfma_f32_16x16x32_bf16 v[68:71], v[174:177], v[236:239], 0
	v_mfma_f32_16x16x32_bf16 v[64:67], v[190:193], v[236:239], 0
	v_mfma_f32_16x16x32_bf16 v[132:135], v[178:181], v[214:217], v[132:135]
	v_mfma_f32_16x16x32_bf16 v[128:131], v[194:197], v[214:217], v[128:131]
	v_mfma_f32_16x16x32_bf16 v[116:119], v[178:181], v[224:227], v[116:119]
	v_mfma_f32_16x16x32_bf16 v[112:115], v[194:197], v[224:227], v[112:115]
	v_mfma_f32_16x16x32_bf16 v[100:103], v[178:181], v[232:235], v[100:103]
	v_mfma_f32_16x16x32_bf16 v[96:99], v[194:197], v[232:235], v[96:99]
	v_mfma_f32_16x16x32_bf16 v[68:71], v[178:181], v[240:243], v[68:71]
	v_mfma_f32_16x16x32_bf16 v[64:67], v[194:197], v[240:243], v[64:67]
	s_setprio 0
	s_barrier
	s_add_i32 s83, s83, s8
	v_lshl_add_u64 v[182:183], s[44:45], 0, v[152:153]
	s_mov_b32 m0, s83
	ds_read_b128 v[210:213], v188 offset:16384
	ds_read_b128 v[214:217], v188 offset:17408
	ds_read_b128 v[218:221], v188 offset:18432
	ds_read_b128 v[224:227], v188 offset:19456
	ds_read_b128 v[228:231], v188 offset:20480
	ds_read_b128 v[232:235], v188 offset:21504
	ds_read_b128 v[236:239], v188 offset:22528
	ds_read_b128 v[240:243], v188 offset:23552
	global_load_lds_dwordx4 v[182:183], off
	s_add_i32 m0, s83, 0x2000
	s_add_u32 s84, s44, 0x40000
	v_lshl_add_u64 v[198:199], s[44:45], 0, v[144:145]
	s_addc_u32 s85, s45, 0
	s_add_i32 s83, s86, s8
	global_load_lds_dwordx4 v[198:199], off
	v_lshl_add_u64 v[244:245], s[84:85], 0, v[152:153]
	s_mov_b32 m0, s83
	v_lshl_add_u64 v[246:247], s[62:63], 0, v[146:147]
	global_load_lds_dwordx4 v[244:245], off
	v_lshl_add_u64 v[244:245], s[84:85], 0, v[144:145]
	s_add_i32 m0, s83, 0x2000
	s_nop 0
	global_load_lds_dwordx4 v[244:245], off
	v_lshl_add_u64 v[244:245], s[62:63], 0, v[148:149]
	s_mov_b32 m0, s59
	s_nop 0
	global_load_lds_dwordx4 v[244:245], off
	s_mov_b32 m0, s66
	s_nop 0
	global_load_lds_dwordx4 v[246:247], off
	s_waitcnt vmcnt(8)
	s_waitcnt lgkmcnt(0)
	s_setprio 1
	s_barrier
	s_waitcnt lgkmcnt(0)
	v_mfma_f32_16x16x32_bf16 v[60:63], v[72:75], v[210:213], 0
	v_mfma_f32_16x16x32_bf16 v[56:59], v[80:83], v[210:213], 0
	v_mfma_f32_16x16x32_bf16 v[44:47], v[72:75], v[218:221], 0
	v_mfma_f32_16x16x32_bf16 v[40:43], v[80:83], v[218:221], 0
	v_mfma_f32_16x16x32_bf16 v[28:31], v[72:75], v[228:231], 0
	v_mfma_f32_16x16x32_bf16 v[24:27], v[80:83], v[228:231], 0
	v_mfma_f32_16x16x32_bf16 v[12:15], v[72:75], v[236:239], 0
	v_mfma_f32_16x16x32_bf16 v[8:11], v[80:83], v[236:239], 0
	v_mfma_f32_16x16x32_bf16 v[60:63], v[76:79], v[214:217], v[60:63]
	v_mfma_f32_16x16x32_bf16 v[56:59], v[88:91], v[214:217], v[56:59]
	v_mfma_f32_16x16x32_bf16 v[44:47], v[76:79], v[224:227], v[44:47]
	v_mfma_f32_16x16x32_bf16 v[40:43], v[88:91], v[224:227], v[40:43]
	v_mfma_f32_16x16x32_bf16 v[28:31], v[76:79], v[232:235], v[28:31]
	v_mfma_f32_16x16x32_bf16 v[24:27], v[88:91], v[232:235], v[24:27]
	v_mfma_f32_16x16x32_bf16 v[12:15], v[76:79], v[240:243], v[12:15]
	v_mfma_f32_16x16x32_bf16 v[8:11], v[88:91], v[240:243], v[8:11]
	s_setprio 0
	s_setprio 1
	v_mfma_f32_16x16x32_bf16 v[52:55], v[174:177], v[210:213], 0
	v_mfma_f32_16x16x32_bf16 v[48:51], v[190:193], v[210:213], 0
	v_mfma_f32_16x16x32_bf16 v[36:39], v[174:177], v[218:221], 0
	v_mfma_f32_16x16x32_bf16 v[32:35], v[190:193], v[218:221], 0
	v_mfma_f32_16x16x32_bf16 v[20:23], v[174:177], v[228:231], 0
	v_mfma_f32_16x16x32_bf16 v[16:19], v[190:193], v[228:231], 0
	v_mfma_f32_16x16x32_bf16 v[4:7], v[174:177], v[236:239], 0
	v_mfma_f32_16x16x32_bf16 v[0:3], v[190:193], v[236:239], 0
	v_mfma_f32_16x16x32_bf16 v[52:55], v[178:181], v[214:217], v[52:55]
	v_mfma_f32_16x16x32_bf16 v[48:51], v[194:197], v[214:217], v[48:51]
	v_mfma_f32_16x16x32_bf16 v[36:39], v[178:181], v[224:227], v[36:39]
	v_mfma_f32_16x16x32_bf16 v[32:35], v[194:197], v[224:227], v[32:35]
	v_mfma_f32_16x16x32_bf16 v[20:23], v[178:181], v[232:235], v[20:23]
	v_mfma_f32_16x16x32_bf16 v[16:19], v[194:197], v[232:235], v[16:19]
	v_mfma_f32_16x16x32_bf16 v[4:7], v[178:181], v[240:243], v[4:7]
	v_mfma_f32_16x16x32_bf16 v[0:3], v[194:197], v[240:243], v[0:3]
	s_setprio 0
	s_barrier
	s_add_i32 s83, 0, 0x18000
	s_add_i32 s84, 0, 0x1c000
	v_add_u32_e32 v88, s83, v185
	v_add_u32_e32 v189, s84, v185
	ds_read_b128 v[72:75], v88
	ds_read_b128 v[76:79], v88 offset:1024
	ds_read_b128 v[80:83], v88 offset:2048
	ds_read_b128 v[88:91], v88 offset:3072
	ds_read_b128 v[174:177], v189
	ds_read_b128 v[178:181], v189 offset:1024
	ds_read_b128 v[190:193], v189 offset:2048
	ds_read_b128 v[194:197], v189 offset:3072
	s_add_u32 s62, s62, 0x40000
	s_addc_u32 s63, s63, 0
	s_mov_b32 m0, s67
	v_lshl_add_u64 v[248:249], s[62:63], 0, v[148:149]
	ds_read_b128 v[210:213], v188 offset:32768
	ds_read_b128 v[214:217], v188 offset:33792
	ds_read_b128 v[218:221], v188 offset:34816
	ds_read_b128 v[224:227], v188 offset:35840
	ds_read_b128 v[228:231], v188 offset:36864
	ds_read_b128 v[232:235], v188 offset:37888
	ds_read_b128 v[236:239], v188 offset:38912
	ds_read_b128 v[240:243], v188 offset:39936
	global_load_lds_dwordx4 v[248:249], off
	v_lshl_add_u64 v[248:249], s[62:63], 0, v[146:147]
	s_mov_b32 m0, s68
	s_nop 0
	global_load_lds_dwordx4 v[248:249], off
	s_waitcnt vmcnt(8)
	s_waitcnt lgkmcnt(0)
	s_setprio 1
	s_barrier
	s_waitcnt lgkmcnt(0)
	v_mfma_f32_16x16x32_bf16 v[140:143], v[72:75], v[210:213], v[140:143]
	v_mfma_f32_16x16x32_bf16 v[136:139], v[80:83], v[210:213], v[136:139]
	v_mfma_f32_16x16x32_bf16 v[124:127], v[72:75], v[218:221], v[124:127]
	v_mfma_f32_16x16x32_bf16 v[120:123], v[80:83], v[218:221], v[120:123]
	v_mfma_f32_16x16x32_bf16 v[108:111], v[72:75], v[228:231], v[108:111]
	v_mfma_f32_16x16x32_bf16 v[104:107], v[80:83], v[228:231], v[104:107]
	v_mfma_f32_16x16x32_bf16 v[92:95], v[72:75], v[236:239], v[92:95]
	v_mfma_f32_16x16x32_bf16 v[84:87], v[80:83], v[236:239], v[84:87]
	v_mfma_f32_16x16x32_bf16 v[140:143], v[76:79], v[214:217], v[140:143]
	v_mfma_f32_16x16x32_bf16 v[136:139], v[88:91], v[214:217], v[136:139]
	v_mfma_f32_16x16x32_bf16 v[124:127], v[76:79], v[224:227], v[124:127]
	v_mfma_f32_16x16x32_bf16 v[120:123], v[88:91], v[224:227], v[120:123]
	v_mfma_f32_16x16x32_bf16 v[108:111], v[76:79], v[232:235], v[108:111]
	v_mfma_f32_16x16x32_bf16 v[104:107], v[88:91], v[232:235], v[104:107]
	v_mfma_f32_16x16x32_bf16 v[92:95], v[76:79], v[240:243], v[92:95]
	v_mfma_f32_16x16x32_bf16 v[84:87], v[88:91], v[240:243], v[84:87]
	s_setprio 0
	s_setprio 1
	v_mfma_f32_16x16x32_bf16 v[132:135], v[174:177], v[210:213], v[132:135]
	v_mfma_f32_16x16x32_bf16 v[128:131], v[190:193], v[210:213], v[128:131]
	v_mfma_f32_16x16x32_bf16 v[116:119], v[174:177], v[218:221], v[116:119]
	v_mfma_f32_16x16x32_bf16 v[112:115], v[190:193], v[218:221], v[112:115]
	v_mfma_f32_16x16x32_bf16 v[100:103], v[174:177], v[228:231], v[100:103]
	v_mfma_f32_16x16x32_bf16 v[96:99], v[190:193], v[228:231], v[96:99]
	v_mfma_f32_16x16x32_bf16 v[68:71], v[174:177], v[236:239], v[68:71]
	v_mfma_f32_16x16x32_bf16 v[64:67], v[190:193], v[236:239], v[64:67]
	v_mfma_f32_16x16x32_bf16 v[132:135], v[178:181], v[214:217], v[132:135]
	v_mfma_f32_16x16x32_bf16 v[128:131], v[194:197], v[214:217], v[128:131]
	v_mfma_f32_16x16x32_bf16 v[116:119], v[178:181], v[224:227], v[116:119]
	v_mfma_f32_16x16x32_bf16 v[112:115], v[194:197], v[224:227], v[112:115]
	v_mfma_f32_16x16x32_bf16 v[100:103], v[178:181], v[232:235], v[100:103]
	v_mfma_f32_16x16x32_bf16 v[96:99], v[194:197], v[232:235], v[96:99]
	v_mfma_f32_16x16x32_bf16 v[68:71], v[178:181], v[240:243], v[68:71]
	v_mfma_f32_16x16x32_bf16 v[64:67], v[194:197], v[240:243], v[64:67]
	s_setprio 0
	s_barrier
	s_add_i32 s62, s83, s8
	v_lshl_add_u64 v[182:183], v[182:183], 0, s[22:23]
	s_mov_b32 m0, s62
	ds_read_b128 v[210:213], v188 offset:49152
	ds_read_b128 v[214:217], v188 offset:50176
	ds_read_b128 v[218:221], v188 offset:51200
	ds_read_b128 v[224:227], v188 offset:52224
	ds_read_b128 v[228:231], v188 offset:53248
	ds_read_b128 v[232:235], v188 offset:54272
	ds_read_b128 v[236:239], v188 offset:55296
	ds_read_b128 v[240:243], v188 offset:56320
	global_load_lds_dwordx4 v[182:183], off
	s_add_i32 m0, s62, 0x2000
	s_add_u32 s44, s44, 0x40080
	v_lshl_add_u64 v[182:183], v[198:199], 0, s[22:23]
	s_addc_u32 s45, s45, 0
	s_add_i32 s62, s84, s8
	global_load_lds_dwordx4 v[182:183], off
	v_lshl_add_u64 v[182:183], s[44:45], 0, v[152:153]
	s_mov_b32 m0, s62
	s_nop 0
	global_load_lds_dwordx4 v[182:183], off
	v_lshl_add_u64 v[182:183], s[44:45], 0, v[144:145]
	s_add_i32 m0, s62, 0x2000
	s_nop 0
	global_load_lds_dwordx4 v[182:183], off
	v_lshl_add_u64 v[182:183], v[244:245], 0, s[22:23]
	s_mov_b32 m0, s69
	s_nop 0
	global_load_lds_dwordx4 v[182:183], off
	v_lshl_add_u64 v[182:183], v[246:247], 0, s[22:23]
	s_mov_b32 m0, s74
	s_nop 0
	global_load_lds_dwordx4 v[182:183], off
	s_waitcnt vmcnt(8)
	s_waitcnt lgkmcnt(0)
	s_setprio 1
	s_barrier
	s_waitcnt lgkmcnt(0)
	v_mfma_f32_16x16x32_bf16 v[60:63], v[72:75], v[210:213], v[60:63]
	v_mfma_f32_16x16x32_bf16 v[56:59], v[80:83], v[210:213], v[56:59]
	v_mfma_f32_16x16x32_bf16 v[44:47], v[72:75], v[218:221], v[44:47]
	v_mfma_f32_16x16x32_bf16 v[40:43], v[80:83], v[218:221], v[40:43]
	v_mfma_f32_16x16x32_bf16 v[28:31], v[72:75], v[228:231], v[28:31]
	v_mfma_f32_16x16x32_bf16 v[24:27], v[80:83], v[228:231], v[24:27]
	v_mfma_f32_16x16x32_bf16 v[12:15], v[72:75], v[236:239], v[12:15]
	v_mfma_f32_16x16x32_bf16 v[8:11], v[80:83], v[236:239], v[8:11]
	v_mfma_f32_16x16x32_bf16 v[60:63], v[76:79], v[214:217], v[60:63]
	v_mfma_f32_16x16x32_bf16 v[56:59], v[88:91], v[214:217], v[56:59]
	v_mfma_f32_16x16x32_bf16 v[44:47], v[76:79], v[224:227], v[44:47]
	v_mfma_f32_16x16x32_bf16 v[40:43], v[88:91], v[224:227], v[40:43]
	v_mfma_f32_16x16x32_bf16 v[28:31], v[76:79], v[232:235], v[28:31]
	v_mfma_f32_16x16x32_bf16 v[24:27], v[88:91], v[232:235], v[24:27]
	v_mfma_f32_16x16x32_bf16 v[12:15], v[76:79], v[240:243], v[12:15]
	v_mfma_f32_16x16x32_bf16 v[8:11], v[88:91], v[240:243], v[8:11]
	s_setprio 0
	s_setprio 1
	v_mfma_f32_16x16x32_bf16 v[52:55], v[174:177], v[210:213], v[52:55]
	v_mfma_f32_16x16x32_bf16 v[48:51], v[190:193], v[210:213], v[48:51]
	v_mfma_f32_16x16x32_bf16 v[36:39], v[174:177], v[218:221], v[36:39]
	v_mfma_f32_16x16x32_bf16 v[32:35], v[190:193], v[218:221], v[32:35]
	v_mfma_f32_16x16x32_bf16 v[20:23], v[174:177], v[228:231], v[20:23]
	v_mfma_f32_16x16x32_bf16 v[16:19], v[190:193], v[228:231], v[16:19]
	v_mfma_f32_16x16x32_bf16 v[4:7], v[174:177], v[236:239], v[4:7]
	v_mfma_f32_16x16x32_bf16 v[0:3], v[190:193], v[236:239], v[0:3]
	v_mfma_f32_16x16x32_bf16 v[52:55], v[178:181], v[214:217], v[52:55]
	v_mfma_f32_16x16x32_bf16 v[48:51], v[194:197], v[214:217], v[48:51]
	v_mfma_f32_16x16x32_bf16 v[36:39], v[178:181], v[224:227], v[36:39]
	v_mfma_f32_16x16x32_bf16 v[32:35], v[194:197], v[224:227], v[32:35]
	v_mfma_f32_16x16x32_bf16 v[20:23], v[178:181], v[232:235], v[20:23]
	v_mfma_f32_16x16x32_bf16 v[16:19], v[194:197], v[232:235], v[16:19]
	v_mfma_f32_16x16x32_bf16 v[4:7], v[178:181], v[240:243], v[4:7]
	v_mfma_f32_16x16x32_bf16 v[0:3], v[194:197], v[240:243], v[0:3]
	s_setprio 0
	s_barrier
	s_add_i32 s82, s82, 2
	s_add_u32 s80, s80, 0x100
	s_addc_u32 s81, s81, 0
	s_add_u32 s48, s48, 0x100
	s_addc_u32 s49, s49, 0
	s_cmp_gt_u32 s82, 13

.LBB0_704:
	s_ashr_i32 s21, s20, 31
	s_lshl_b64 s[48:49], s[20:21], 18
	v_readlane_b32 s19, v254, 14
	s_add_u32 s48, s19, s48
	v_readlane_b32 s19, v254, 15
	s_addc_u32 s49, s19, s49
	s_and_b64 s[50:51], s[46:47], exec
	s_cselect_b32 s21, s49, s45
	s_cselect_b32 s78, s48, s44
	s_ashr_i32 s19, s18, 31
	s_lshl_b64 s[50:51], s[18:19], 18
	v_readlane_b32 s19, v254, 10
	s_add_u32 s50, s19, s50
	v_readlane_b32 s19, v254, 11
	s_addc_u32 s51, s19, s51
	s_and_b64 s[62:63], s[46:47], exec
	s_cselect_b32 s19, s51, s61
	s_cselect_b32 s79, s50, s60
	s_add_u32 s80, s60, 0x100
	s_addc_u32 s81, s61, 0
	s_add_u32 s60, s44, 0x20080
	s_addc_u32 s61, s45, 0
	s_mov_b32 s82, -2
	s_add_u32 s44, s60, 0xfffe0080
	s_addc_u32 s45, s61, -1
	s_add_i32 s83, 0, 0x10000
	s_cmp_eq_u32 s82, 4
	s_cselect_b32 s63, s21, s45
	s_cselect_b32 s62, s78, s44
	s_cselect_b32 s45, s19, s81
	s_cselect_b32 s44, s79, s80
	s_add_i32 s86, 0, 0x14000
	v_add_u32_e32 v140, s83, v195
	v_add_u32_e32 v186, s86, v195
	ds_read_b128 v[124:127], v140
	ds_read_b128 v[132:135], v140 offset:1024
	ds_read_b128 v[136:139], v140 offset:2048
	ds_read_b128 v[140:143], v140 offset:3072
	ds_read_b128 v[144:147], v186
	ds_read_b128 v[148:151], v186 offset:1024
	ds_read_b128 v[182:185], v186 offset:2048
	ds_read_b128 v[186:189], v186 offset:3072
	v_lshl_add_u64 v[198:199], s[60:61], 0, v[180:181]
	s_add_i32 m0, s59, 0xc000
	ds_read_b128 v[190:193], v197
	ds_read_b128 v[210:213], v197 offset:1024
	ds_read_b128 v[214:217], v197 offset:2048
	ds_read_b128 v[218:221], v197 offset:3072
	ds_read_b128 v[224:227], v197 offset:4096
	ds_read_b128 v[228:231], v197 offset:5120
	ds_read_b128 v[232:235], v197 offset:6144
	ds_read_b128 v[236:239], v197 offset:7168
	global_load_lds_dwordx4 v[198:199], off
	v_lshl_add_u64 v[198:199], s[60:61], 0, v[178:179]
	s_add_i32 m0, s59, 0xe000
	s_nop 0
	global_load_lds_dwordx4 v[198:199], off
	s_waitcnt vmcnt(8)
	s_waitcnt lgkmcnt(0)
	s_setprio 1
	s_barrier
	s_waitcnt lgkmcnt(0)
	v_mfma_f32_16x16x32_bf16 v[128:131], v[124:127], v[190:193], 0
	v_mfma_f32_16x16x32_bf16 v[120:123], v[136:139], v[190:193], 0
	v_mfma_f32_16x16x32_bf16 v[108:111], v[124:127], v[214:217], 0
	v_mfma_f32_16x16x32_bf16 v[104:107], v[136:139], v[214:217], 0
	v_mfma_f32_16x16x32_bf16 v[92:95], v[124:127], v[224:227], 0
	v_mfma_f32_16x16x32_bf16 v[88:91], v[136:139], v[224:227], 0
	v_mfma_f32_16x16x32_bf16 v[76:79], v[124:127], v[232:235], 0
	v_mfma_f32_16x16x32_bf16 v[72:75], v[136:139], v[232:235], 0
	v_mfma_f32_16x16x32_bf16 v[128:131], v[132:135], v[210:213], v[128:131]
	v_mfma_f32_16x16x32_bf16 v[120:123], v[140:143], v[210:213], v[120:123]
	v_mfma_f32_16x16x32_bf16 v[108:111], v[132:135], v[218:221], v[108:111]
	v_mfma_f32_16x16x32_bf16 v[104:107], v[140:143], v[218:221], v[104:107]
	v_mfma_f32_16x16x32_bf16 v[92:95], v[132:135], v[228:231], v[92:95]
	v_mfma_f32_16x16x32_bf16 v[88:91], v[140:143], v[228:231], v[88:91]
	v_mfma_f32_16x16x32_bf16 v[76:79], v[132:135], v[236:239], v[76:79]
	v_mfma_f32_16x16x32_bf16 v[72:75], v[140:143], v[236:239], v[72:75]
	s_setprio 0
	s_setprio 1
	v_mfma_f32_16x16x32_bf16 v[116:119], v[144:147], v[190:193], 0
	v_mfma_f32_16x16x32_bf16 v[112:115], v[182:185], v[190:193], 0
	v_mfma_f32_16x16x32_bf16 v[100:103], v[144:147], v[214:217], 0
	v_mfma_f32_16x16x32_bf16 v[96:99], v[182:185], v[214:217], 0
	v_mfma_f32_16x16x32_bf16 v[84:87], v[144:147], v[224:227], 0
	v_mfma_f32_16x16x32_bf16 v[80:83], v[182:185], v[224:227], 0
	v_mfma_f32_16x16x32_bf16 v[68:71], v[144:147], v[232:235], 0
	v_mfma_f32_16x16x32_bf16 v[64:67], v[182:185], v[232:235], 0
	v_mfma_f32_16x16x32_bf16 v[116:119], v[148:151], v[210:213], v[116:119]
	v_mfma_f32_16x16x32_bf16 v[112:115], v[186:189], v[210:213], v[112:115]
	v_mfma_f32_16x16x32_bf16 v[100:103], v[148:151], v[218:221], v[100:103]
	v_mfma_f32_16x16x32_bf16 v[96:99], v[186:189], v[218:221], v[96:99]
	v_mfma_f32_16x16x32_bf16 v[84:87], v[148:151], v[228:231], v[84:87]
	v_mfma_f32_16x16x32_bf16 v[80:83], v[186:189], v[228:231], v[80:83]
	v_mfma_f32_16x16x32_bf16 v[68:71], v[148:151], v[236:239], v[68:71]
	v_mfma_f32_16x16x32_bf16 v[64:67], v[186:189], v[236:239], v[64:67]
	s_setprio 0
	s_barrier
	s_add_i32 s83, s83, s8
	v_lshl_add_u64 v[198:199], s[44:45], 0, v[152:153]
	s_mov_b32 m0, s83
	ds_read_b128 v[190:193], v197 offset:16384
	ds_read_b128 v[210:213], v197 offset:17408
	ds_read_b128 v[214:217], v197 offset:18432
	ds_read_b128 v[218:221], v197 offset:19456
	ds_read_b128 v[224:227], v197 offset:20480
	ds_read_b128 v[228:231], v197 offset:21504
	ds_read_b128 v[232:235], v197 offset:22528
	ds_read_b128 v[236:239], v197 offset:23552
	global_load_lds_dwordx4 v[198:199], off
	s_add_i32 m0, s83, 0x2000
	s_add_u32 s84, s44, 0x20000
	v_lshl_add_u64 v[240:241], s[44:45], 0, v[172:173]
	s_addc_u32 s85, s45, 0
	s_add_i32 s83, s86, s8
	global_load_lds_dwordx4 v[240:241], off
	v_lshl_add_u64 v[242:243], s[84:85], 0, v[152:153]
	s_mov_b32 m0, s83
	v_lshl_add_u64 v[244:245], s[62:63], 0, v[174:175]
	global_load_lds_dwordx4 v[242:243], off
	v_lshl_add_u64 v[242:243], s[84:85], 0, v[172:173]
	s_add_i32 m0, s83, 0x2000
	s_nop 0
	global_load_lds_dwordx4 v[242:243], off
	v_lshl_add_u64 v[242:243], s[62:63], 0, v[176:177]
	s_mov_b32 m0, s59
	s_nop 0
	global_load_lds_dwordx4 v[242:243], off
	s_mov_b32 m0, s66
	s_nop 0
	global_load_lds_dwordx4 v[244:245], off
	s_waitcnt vmcnt(8)
	s_waitcnt lgkmcnt(0)
	s_setprio 1
	s_barrier
	s_waitcnt lgkmcnt(0)
	v_mfma_f32_16x16x32_bf16 v[60:63], v[124:127], v[190:193], 0
	v_mfma_f32_16x16x32_bf16 v[56:59], v[136:139], v[190:193], 0
	v_mfma_f32_16x16x32_bf16 v[48:51], v[124:127], v[214:217], 0
	v_mfma_f32_16x16x32_bf16 v[40:43], v[136:139], v[214:217], 0
	v_mfma_f32_16x16x32_bf16 v[32:35], v[124:127], v[224:227], 0
	v_mfma_f32_16x16x32_bf16 v[24:27], v[136:139], v[224:227], 0
	v_mfma_f32_16x16x32_bf16 v[16:19], v[124:127], v[232:235], 0
	v_mfma_f32_16x16x32_bf16 v[8:11], v[136:139], v[232:235], 0
	v_mfma_f32_16x16x32_bf16 v[60:63], v[132:135], v[210:213], v[60:63]
	v_mfma_f32_16x16x32_bf16 v[56:59], v[140:143], v[210:213], v[56:59]
	v_mfma_f32_16x16x32_bf16 v[48:51], v[132:135], v[218:221], v[48:51]
	v_mfma_f32_16x16x32_bf16 v[40:43], v[140:143], v[218:221], v[40:43]
	v_mfma_f32_16x16x32_bf16 v[32:35], v[132:135], v[228:231], v[32:35]
	v_mfma_f32_16x16x32_bf16 v[24:27], v[140:143], v[228:231], v[24:27]
	v_mfma_f32_16x16x32_bf16 v[16:19], v[132:135], v[236:239], v[16:19]
	v_mfma_f32_16x16x32_bf16 v[8:11], v[140:143], v[236:239], v[8:11]
	s_setprio 0
	s_setprio 1
	v_mfma_f32_16x16x32_bf16 v[52:55], v[144:147], v[190:193], 0
	v_mfma_f32_16x16x32_bf16 v[44:47], v[182:185], v[190:193], 0
	v_mfma_f32_16x16x32_bf16 v[36:39], v[144:147], v[214:217], 0
	v_mfma_f32_16x16x32_bf16 v[28:31], v[182:185], v[214:217], 0
	v_mfma_f32_16x16x32_bf16 v[20:23], v[144:147], v[224:227], 0
	v_mfma_f32_16x16x32_bf16 v[12:15], v[182:185], v[224:227], 0
	v_mfma_f32_16x16x32_bf16 v[4:7], v[144:147], v[232:235], 0
	v_mfma_f32_16x16x32_bf16 v[0:3], v[182:185], v[232:235], 0
	v_mfma_f32_16x16x32_bf16 v[52:55], v[148:151], v[210:213], v[52:55]
	v_mfma_f32_16x16x32_bf16 v[44:47], v[186:189], v[210:213], v[44:47]
	v_mfma_f32_16x16x32_bf16 v[36:39], v[148:151], v[218:221], v[36:39]
	v_mfma_f32_16x16x32_bf16 v[28:31], v[186:189], v[218:221], v[28:31]
	v_mfma_f32_16x16x32_bf16 v[20:23], v[148:151], v[228:231], v[20:23]
	v_mfma_f32_16x16x32_bf16 v[12:15], v[186:189], v[228:231], v[12:15]
	v_mfma_f32_16x16x32_bf16 v[4:7], v[148:151], v[236:239], v[4:7]
	v_mfma_f32_16x16x32_bf16 v[0:3], v[186:189], v[236:239], v[0:3]
	s_setprio 0
	s_barrier
	s_add_i32 s83, 0, 0x18000
	s_add_i32 s84, 0, 0x1c000
	v_add_u32_e32 v140, s83, v195
	v_add_u32_e32 v186, s84, v195
	ds_read_b128 v[124:127], v140
	ds_read_b128 v[132:135], v140 offset:1024
	ds_read_b128 v[136:139], v140 offset:2048
	ds_read_b128 v[140:143], v140 offset:3072
	ds_read_b128 v[144:147], v186
	ds_read_b128 v[148:151], v186 offset:1024
	ds_read_b128 v[182:185], v186 offset:2048
	ds_read_b128 v[186:189], v186 offset:3072
	s_add_u32 s62, s62, 0x20000
	s_addc_u32 s63, s63, 0
	s_mov_b32 m0, s67
	v_lshl_add_u64 v[246:247], s[62:63], 0, v[176:177]
	ds_read_b128 v[190:193], v197 offset:32768
	ds_read_b128 v[210:213], v197 offset:33792
	ds_read_b128 v[214:217], v197 offset:34816
	ds_read_b128 v[218:221], v197 offset:35840
	ds_read_b128 v[224:227], v197 offset:36864
	ds_read_b128 v[228:231], v197 offset:37888
	ds_read_b128 v[232:235], v197 offset:38912
	ds_read_b128 v[236:239], v197 offset:39936
	global_load_lds_dwordx4 v[246:247], off
	v_lshl_add_u64 v[246:247], s[62:63], 0, v[174:175]
	s_mov_b32 m0, s68
	s_nop 0
	global_load_lds_dwordx4 v[246:247], off
	s_waitcnt vmcnt(8)
	s_waitcnt lgkmcnt(0)
	s_setprio 1
	s_barrier
	s_waitcnt lgkmcnt(0)
	v_mfma_f32_16x16x32_bf16 v[128:131], v[124:127], v[190:193], v[128:131]
	v_mfma_f32_16x16x32_bf16 v[120:123], v[136:139], v[190:193], v[120:123]
	v_mfma_f32_16x16x32_bf16 v[108:111], v[124:127], v[214:217], v[108:111]
	v_mfma_f32_16x16x32_bf16 v[104:107], v[136:139], v[214:217], v[104:107]
	v_mfma_f32_16x16x32_bf16 v[92:95], v[124:127], v[224:227], v[92:95]
	v_mfma_f32_16x16x32_bf16 v[88:91], v[136:139], v[224:227], v[88:91]
	v_mfma_f32_16x16x32_bf16 v[76:79], v[124:127], v[232:235], v[76:79]
	v_mfma_f32_16x16x32_bf16 v[72:75], v[136:139], v[232:235], v[72:75]
	v_mfma_f32_16x16x32_bf16 v[128:131], v[132:135], v[210:213], v[128:131]
	v_mfma_f32_16x16x32_bf16 v[120:123], v[140:143], v[210:213], v[120:123]
	v_mfma_f32_16x16x32_bf16 v[108:111], v[132:135], v[218:221], v[108:111]
	v_mfma_f32_16x16x32_bf16 v[104:107], v[140:143], v[218:221], v[104:107]
	v_mfma_f32_16x16x32_bf16 v[92:95], v[132:135], v[228:231], v[92:95]
	v_mfma_f32_16x16x32_bf16 v[88:91], v[140:143], v[228:231], v[88:91]
	v_mfma_f32_16x16x32_bf16 v[76:79], v[132:135], v[236:239], v[76:79]
	v_mfma_f32_16x16x32_bf16 v[72:75], v[140:143], v[236:239], v[72:75]
	s_setprio 0
	s_setprio 1
	v_mfma_f32_16x16x32_bf16 v[116:119], v[144:147], v[190:193], v[116:119]
	v_mfma_f32_16x16x32_bf16 v[112:115], v[182:185], v[190:193], v[112:115]
	v_mfma_f32_16x16x32_bf16 v[100:103], v[144:147], v[214:217], v[100:103]
	v_mfma_f32_16x16x32_bf16 v[96:99], v[182:185], v[214:217], v[96:99]
	v_mfma_f32_16x16x32_bf16 v[84:87], v[144:147], v[224:227], v[84:87]
	v_mfma_f32_16x16x32_bf16 v[80:83], v[182:185], v[224:227], v[80:83]
	v_mfma_f32_16x16x32_bf16 v[68:71], v[144:147], v[232:235], v[68:71]
	v_mfma_f32_16x16x32_bf16 v[64:67], v[182:185], v[232:235], v[64:67]
	v_mfma_f32_16x16x32_bf16 v[116:119], v[148:151], v[210:213], v[116:119]
	v_mfma_f32_16x16x32_bf16 v[112:115], v[186:189], v[210:213], v[112:115]
	v_mfma_f32_16x16x32_bf16 v[100:103], v[148:151], v[218:221], v[100:103]
	v_mfma_f32_16x16x32_bf16 v[96:99], v[186:189], v[218:221], v[96:99]
	v_mfma_f32_16x16x32_bf16 v[84:87], v[148:151], v[228:231], v[84:87]
	v_mfma_f32_16x16x32_bf16 v[80:83], v[186:189], v[228:231], v[80:83]
	v_mfma_f32_16x16x32_bf16 v[68:71], v[148:151], v[236:239], v[68:71]
	v_mfma_f32_16x16x32_bf16 v[64:67], v[186:189], v[236:239], v[64:67]
	s_setprio 0
	s_barrier
	s_add_i32 s62, s83, s8
	v_lshl_add_u64 v[198:199], v[198:199], 0, s[22:23]
	s_mov_b32 m0, s62
	ds_read_b128 v[190:193], v197 offset:49152
	ds_read_b128 v[210:213], v197 offset:50176
	ds_read_b128 v[214:217], v197 offset:51200
	ds_read_b128 v[218:221], v197 offset:52224
	ds_read_b128 v[224:227], v197 offset:53248
	ds_read_b128 v[228:231], v197 offset:54272
	ds_read_b128 v[232:235], v197 offset:55296
	ds_read_b128 v[236:239], v197 offset:56320
	global_load_lds_dwordx4 v[198:199], off
	s_add_i32 m0, s62, 0x2000
	s_add_u32 s44, s44, 0x20080
	v_lshl_add_u64 v[198:199], v[240:241], 0, s[22:23]
	s_addc_u32 s45, s45, 0
	s_add_i32 s62, s84, s8
	global_load_lds_dwordx4 v[198:199], off
	v_lshl_add_u64 v[198:199], s[44:45], 0, v[152:153]
	s_mov_b32 m0, s62
	s_nop 0
	global_load_lds_dwordx4 v[198:199], off
	v_lshl_add_u64 v[198:199], s[44:45], 0, v[172:173]
	s_add_i32 m0, s62, 0x2000
	s_nop 0
	global_load_lds_dwordx4 v[198:199], off
	v_lshl_add_u64 v[198:199], v[242:243], 0, s[22:23]
	s_mov_b32 m0, s69
	s_nop 0
	global_load_lds_dwordx4 v[198:199], off
	v_lshl_add_u64 v[198:199], v[244:245], 0, s[22:23]
	s_mov_b32 m0, s74
	s_nop 0
	global_load_lds_dwordx4 v[198:199], off
	s_waitcnt vmcnt(8)
	s_waitcnt lgkmcnt(0)
	s_setprio 1
	s_barrier
	s_waitcnt lgkmcnt(0)
	v_mfma_f32_16x16x32_bf16 v[60:63], v[124:127], v[190:193], v[60:63]
	v_mfma_f32_16x16x32_bf16 v[56:59], v[136:139], v[190:193], v[56:59]
	v_mfma_f32_16x16x32_bf16 v[48:51], v[124:127], v[214:217], v[48:51]
	v_mfma_f32_16x16x32_bf16 v[40:43], v[136:139], v[214:217], v[40:43]
	v_mfma_f32_16x16x32_bf16 v[32:35], v[124:127], v[224:227], v[32:35]
	v_mfma_f32_16x16x32_bf16 v[24:27], v[136:139], v[224:227], v[24:27]
	v_mfma_f32_16x16x32_bf16 v[16:19], v[124:127], v[232:235], v[16:19]
	v_mfma_f32_16x16x32_bf16 v[8:11], v[136:139], v[232:235], v[8:11]
	v_mfma_f32_16x16x32_bf16 v[60:63], v[132:135], v[210:213], v[60:63]
	v_mfma_f32_16x16x32_bf16 v[56:59], v[140:143], v[210:213], v[56:59]
	v_mfma_f32_16x16x32_bf16 v[48:51], v[132:135], v[218:221], v[48:51]
	v_mfma_f32_16x16x32_bf16 v[40:43], v[140:143], v[218:221], v[40:43]
	v_mfma_f32_16x16x32_bf16 v[32:35], v[132:135], v[228:231], v[32:35]
	v_mfma_f32_16x16x32_bf16 v[24:27], v[140:143], v[228:231], v[24:27]
	v_mfma_f32_16x16x32_bf16 v[16:19], v[132:135], v[236:239], v[16:19]
	v_mfma_f32_16x16x32_bf16 v[8:11], v[140:143], v[236:239], v[8:11]
	s_setprio 0
	s_setprio 1
	v_mfma_f32_16x16x32_bf16 v[52:55], v[144:147], v[190:193], v[52:55]
	v_mfma_f32_16x16x32_bf16 v[44:47], v[182:185], v[190:193], v[44:47]
	v_mfma_f32_16x16x32_bf16 v[36:39], v[144:147], v[214:217], v[36:39]
	v_mfma_f32_16x16x32_bf16 v[28:31], v[182:185], v[214:217], v[28:31]
	v_mfma_f32_16x16x32_bf16 v[20:23], v[144:147], v[224:227], v[20:23]
	v_mfma_f32_16x16x32_bf16 v[12:15], v[182:185], v[224:227], v[12:15]
	v_mfma_f32_16x16x32_bf16 v[4:7], v[144:147], v[232:235], v[4:7]
	v_mfma_f32_16x16x32_bf16 v[0:3], v[182:185], v[232:235], v[0:3]
	v_mfma_f32_16x16x32_bf16 v[52:55], v[148:151], v[210:213], v[52:55]
	v_mfma_f32_16x16x32_bf16 v[44:47], v[186:189], v[210:213], v[44:47]
	v_mfma_f32_16x16x32_bf16 v[36:39], v[148:151], v[218:221], v[36:39]
	v_mfma_f32_16x16x32_bf16 v[28:31], v[186:189], v[218:221], v[28:31]
	v_mfma_f32_16x16x32_bf16 v[20:23], v[148:151], v[228:231], v[20:23]
	v_mfma_f32_16x16x32_bf16 v[12:15], v[186:189], v[228:231], v[12:15]
	v_mfma_f32_16x16x32_bf16 v[4:7], v[148:151], v[236:239], v[4:7]
	v_mfma_f32_16x16x32_bf16 v[0:3], v[186:189], v[236:239], v[0:3]
	s_setprio 0
	s_barrier
	s_add_i32 s82, s82, 2
	s_add_u32 s80, s80, 0x100
	s_addc_u32 s81, s81, 0
	s_add_u32 s60, s60, 0x100
	s_addc_u32 s61, s61, 0
	s_cmp_gt_u32 s82, 5

.LBB0_724:
	s_ashr_i32 s21, s20, 31
	s_lshl_b64 s[48:49], s[20:21], 18
	v_readlane_b32 s19, v254, 28
	s_add_u32 s48, s19, s48
	v_readlane_b32 s19, v254, 29
	s_addc_u32 s49, s19, s49
	s_and_b64 s[50:51], s[46:47], exec
	s_cselect_b32 s21, s49, s45
	s_cselect_b32 s78, s48, s44
	s_ashr_i32 s19, s18, 31
	s_lshl_b64 s[50:51], s[18:19], 18
	v_readlane_b32 s19, v254, 24
	s_add_u32 s50, s19, s50
	v_readlane_b32 s19, v254, 25
	s_addc_u32 s51, s19, s51
	s_and_b64 s[62:63], s[46:47], exec
	s_cselect_b32 s19, s51, s61
	s_cselect_b32 s79, s50, s60
	s_add_u32 s80, s60, 0x100
	s_addc_u32 s81, s61, 0
	s_add_u32 s60, s44, 0x20080
	s_addc_u32 s61, s45, 0
	s_mov_b32 s82, -2
	s_add_u32 s44, s60, 0xfffe0080
	s_addc_u32 s45, s61, -1
	s_add_i32 s83, 0, 0x10000
	s_cmp_eq_u32 s82, 4
	s_cselect_b32 s63, s21, s45
	s_cselect_b32 s62, s78, s44
	s_cselect_b32 s45, s19, s81
	s_cselect_b32 s44, s79, s80
	s_add_i32 s86, 0, 0x14000
	v_add_u32_e32 v140, s83, v181
	v_add_u32_e32 v178, s86, v181
	ds_read_b128 v[128:131], v140
	ds_read_b128 v[132:135], v140 offset:1024
	ds_read_b128 v[136:139], v140 offset:2048
	ds_read_b128 v[140:143], v140 offset:3072
	ds_read_b128 v[174:177], v178
	ds_read_b128 v[184:187], v178 offset:1024
	ds_read_b128 v[188:191], v178 offset:2048
	ds_read_b128 v[192:195], v178 offset:3072
	v_lshl_add_u64 v[178:179], s[60:61], 0, v[172:173]
	s_add_i32 m0, s59, 0xc000
	ds_read_b128 v[196:199], v183
	ds_read_b128 v[210:213], v183 offset:1024
	ds_read_b128 v[214:217], v183 offset:2048
	ds_read_b128 v[218:221], v183 offset:3072
	ds_read_b128 v[224:227], v183 offset:4096
	ds_read_b128 v[228:231], v183 offset:5120
	ds_read_b128 v[232:235], v183 offset:6144
	ds_read_b128 v[236:239], v183 offset:7168
	global_load_lds_dwordx4 v[178:179], off
	v_lshl_add_u64 v[178:179], s[60:61], 0, v[150:151]
	s_add_i32 m0, s59, 0xe000
	s_nop 0
	global_load_lds_dwordx4 v[178:179], off
	s_waitcnt vmcnt(8)
	s_waitcnt lgkmcnt(0)
	s_setprio 1
	s_barrier
	s_waitcnt lgkmcnt(0)
	v_mfma_f32_16x16x32_bf16 v[124:127], v[128:131], v[196:199], 0
	v_mfma_f32_16x16x32_bf16 v[120:123], v[136:139], v[196:199], 0
	v_mfma_f32_16x16x32_bf16 v[108:111], v[128:131], v[214:217], 0
	v_mfma_f32_16x16x32_bf16 v[104:107], v[136:139], v[214:217], 0
	v_mfma_f32_16x16x32_bf16 v[92:95], v[128:131], v[224:227], 0
	v_mfma_f32_16x16x32_bf16 v[88:91], v[136:139], v[224:227], 0
	v_mfma_f32_16x16x32_bf16 v[76:79], v[128:131], v[232:235], 0
	v_mfma_f32_16x16x32_bf16 v[72:75], v[136:139], v[232:235], 0
	v_mfma_f32_16x16x32_bf16 v[124:127], v[132:135], v[210:213], v[124:127]
	v_mfma_f32_16x16x32_bf16 v[120:123], v[140:143], v[210:213], v[120:123]
	v_mfma_f32_16x16x32_bf16 v[108:111], v[132:135], v[218:221], v[108:111]
	v_mfma_f32_16x16x32_bf16 v[104:107], v[140:143], v[218:221], v[104:107]
	v_mfma_f32_16x16x32_bf16 v[92:95], v[132:135], v[228:231], v[92:95]
	v_mfma_f32_16x16x32_bf16 v[88:91], v[140:143], v[228:231], v[88:91]
	v_mfma_f32_16x16x32_bf16 v[76:79], v[132:135], v[236:239], v[76:79]
	v_mfma_f32_16x16x32_bf16 v[72:75], v[140:143], v[236:239], v[72:75]
	s_setprio 0
	s_setprio 1
	v_mfma_f32_16x16x32_bf16 v[116:119], v[174:177], v[196:199], 0
	v_mfma_f32_16x16x32_bf16 v[112:115], v[188:191], v[196:199], 0
	v_mfma_f32_16x16x32_bf16 v[100:103], v[174:177], v[214:217], 0
	v_mfma_f32_16x16x32_bf16 v[96:99], v[188:191], v[214:217], 0
	v_mfma_f32_16x16x32_bf16 v[84:87], v[174:177], v[224:227], 0
	v_mfma_f32_16x16x32_bf16 v[80:83], v[188:191], v[224:227], 0
	v_mfma_f32_16x16x32_bf16 v[68:71], v[174:177], v[232:235], 0
	v_mfma_f32_16x16x32_bf16 v[64:67], v[188:191], v[232:235], 0
	v_mfma_f32_16x16x32_bf16 v[116:119], v[184:187], v[210:213], v[116:119]
	v_mfma_f32_16x16x32_bf16 v[112:115], v[192:195], v[210:213], v[112:115]
	v_mfma_f32_16x16x32_bf16 v[100:103], v[184:187], v[218:221], v[100:103]
	v_mfma_f32_16x16x32_bf16 v[96:99], v[192:195], v[218:221], v[96:99]
	v_mfma_f32_16x16x32_bf16 v[84:87], v[184:187], v[228:231], v[84:87]
	v_mfma_f32_16x16x32_bf16 v[80:83], v[192:195], v[228:231], v[80:83]
	v_mfma_f32_16x16x32_bf16 v[68:71], v[184:187], v[236:239], v[68:71]
	v_mfma_f32_16x16x32_bf16 v[64:67], v[192:195], v[236:239], v[64:67]
	s_setprio 0
	s_barrier
	s_add_i32 s83, s83, s8
	v_lshl_add_u64 v[178:179], s[44:45], 0, v[152:153]
	s_mov_b32 m0, s83
	ds_read_b128 v[196:199], v183 offset:16384
	ds_read_b128 v[210:213], v183 offset:17408
	ds_read_b128 v[214:217], v183 offset:18432
	ds_read_b128 v[218:221], v183 offset:19456
	ds_read_b128 v[224:227], v183 offset:20480
	ds_read_b128 v[228:231], v183 offset:21504
	ds_read_b128 v[232:235], v183 offset:22528
	ds_read_b128 v[236:239], v183 offset:23552
	global_load_lds_dwordx4 v[178:179], off
	s_add_i32 m0, s83, 0x2000
	s_add_u32 s84, s44, 0x20000
	v_lshl_add_u64 v[240:241], s[44:45], 0, v[144:145]
	s_addc_u32 s85, s45, 0
	s_add_i32 s83, s86, s8
	global_load_lds_dwordx4 v[240:241], off
	v_lshl_add_u64 v[242:243], s[84:85], 0, v[152:153]
	s_mov_b32 m0, s83
	v_lshl_add_u64 v[244:245], s[62:63], 0, v[146:147]
	global_load_lds_dwordx4 v[242:243], off
	v_lshl_add_u64 v[242:243], s[84:85], 0, v[144:145]
	s_add_i32 m0, s83, 0x2000
	s_nop 0
	global_load_lds_dwordx4 v[242:243], off
	v_lshl_add_u64 v[242:243], s[62:63], 0, v[148:149]
	s_mov_b32 m0, s59
	s_nop 0
	global_load_lds_dwordx4 v[242:243], off
	s_mov_b32 m0, s66
	s_nop 0
	global_load_lds_dwordx4 v[244:245], off
	s_waitcnt vmcnt(8)
	s_waitcnt lgkmcnt(0)
	s_setprio 1
	s_barrier
	s_waitcnt lgkmcnt(0)
	v_mfma_f32_16x16x32_bf16 v[60:63], v[128:131], v[196:199], 0
	v_mfma_f32_16x16x32_bf16 v[56:59], v[136:139], v[196:199], 0
	v_mfma_f32_16x16x32_bf16 v[44:47], v[128:131], v[214:217], 0
	v_mfma_f32_16x16x32_bf16 v[40:43], v[136:139], v[214:217], 0
	v_mfma_f32_16x16x32_bf16 v[28:31], v[128:131], v[224:227], 0
	v_mfma_f32_16x16x32_bf16 v[24:27], v[136:139], v[224:227], 0
	v_mfma_f32_16x16x32_bf16 v[12:15], v[128:131], v[232:235], 0
	v_mfma_f32_16x16x32_bf16 v[8:11], v[136:139], v[232:235], 0
	v_mfma_f32_16x16x32_bf16 v[60:63], v[132:135], v[210:213], v[60:63]
	v_mfma_f32_16x16x32_bf16 v[56:59], v[140:143], v[210:213], v[56:59]
	v_mfma_f32_16x16x32_bf16 v[44:47], v[132:135], v[218:221], v[44:47]
	v_mfma_f32_16x16x32_bf16 v[40:43], v[140:143], v[218:221], v[40:43]
	v_mfma_f32_16x16x32_bf16 v[28:31], v[132:135], v[228:231], v[28:31]
	v_mfma_f32_16x16x32_bf16 v[24:27], v[140:143], v[228:231], v[24:27]
	v_mfma_f32_16x16x32_bf16 v[12:15], v[132:135], v[236:239], v[12:15]
	v_mfma_f32_16x16x32_bf16 v[8:11], v[140:143], v[236:239], v[8:11]
	s_setprio 0
	s_setprio 1
	v_mfma_f32_16x16x32_bf16 v[52:55], v[174:177], v[196:199], 0
	v_mfma_f32_16x16x32_bf16 v[48:51], v[188:191], v[196:199], 0
	v_mfma_f32_16x16x32_bf16 v[36:39], v[174:177], v[214:217], 0
	v_mfma_f32_16x16x32_bf16 v[32:35], v[188:191], v[214:217], 0
	v_mfma_f32_16x16x32_bf16 v[20:23], v[174:177], v[224:227], 0
	v_mfma_f32_16x16x32_bf16 v[16:19], v[188:191], v[224:227], 0
	v_mfma_f32_16x16x32_bf16 v[4:7], v[174:177], v[232:235], 0
	v_mfma_f32_16x16x32_bf16 v[0:3], v[188:191], v[232:235], 0
	v_mfma_f32_16x16x32_bf16 v[52:55], v[184:187], v[210:213], v[52:55]
	v_mfma_f32_16x16x32_bf16 v[48:51], v[192:195], v[210:213], v[48:51]
	v_mfma_f32_16x16x32_bf16 v[36:39], v[184:187], v[218:221], v[36:39]
	v_mfma_f32_16x16x32_bf16 v[32:35], v[192:195], v[218:221], v[32:35]
	v_mfma_f32_16x16x32_bf16 v[20:23], v[184:187], v[228:231], v[20:23]
	v_mfma_f32_16x16x32_bf16 v[16:19], v[192:195], v[228:231], v[16:19]
	v_mfma_f32_16x16x32_bf16 v[4:7], v[184:187], v[236:239], v[4:7]
	v_mfma_f32_16x16x32_bf16 v[0:3], v[192:195], v[236:239], v[0:3]
	s_setprio 0
	s_barrier
	s_add_i32 s83, 0, 0x18000
	s_add_i32 s84, 0, 0x1c000
	v_add_u32_e32 v140, s83, v181
	v_add_u32_e32 v192, s84, v181
	ds_read_b128 v[128:131], v140
	ds_read_b128 v[132:135], v140 offset:1024
	ds_read_b128 v[136:139], v140 offset:2048
	ds_read_b128 v[140:143], v140 offset:3072
	ds_read_b128 v[174:177], v192
	ds_read_b128 v[184:187], v192 offset:1024
	ds_read_b128 v[188:191], v192 offset:2048
	ds_read_b128 v[192:195], v192 offset:3072
	s_add_u32 s62, s62, 0x20000
	s_addc_u32 s63, s63, 0
	s_mov_b32 m0, s67
	v_lshl_add_u64 v[246:247], s[62:63], 0, v[148:149]
	ds_read_b128 v[196:199], v183 offset:32768
	ds_read_b128 v[210:213], v183 offset:33792
	ds_read_b128 v[214:217], v183 offset:34816
	ds_read_b128 v[218:221], v183 offset:35840
	ds_read_b128 v[224:227], v183 offset:36864
	ds_read_b128 v[228:231], v183 offset:37888
	ds_read_b128 v[232:235], v183 offset:38912
	ds_read_b128 v[236:239], v183 offset:39936
	global_load_lds_dwordx4 v[246:247], off
	v_lshl_add_u64 v[246:247], s[62:63], 0, v[146:147]
	s_mov_b32 m0, s68
	s_nop 0
	global_load_lds_dwordx4 v[246:247], off
	s_waitcnt vmcnt(8)
	s_waitcnt lgkmcnt(0)
	s_setprio 1
	s_barrier
	s_waitcnt lgkmcnt(0)
	v_mfma_f32_16x16x32_bf16 v[124:127], v[128:131], v[196:199], v[124:127]
	v_mfma_f32_16x16x32_bf16 v[120:123], v[136:139], v[196:199], v[120:123]
	v_mfma_f32_16x16x32_bf16 v[108:111], v[128:131], v[214:217], v[108:111]
	v_mfma_f32_16x16x32_bf16 v[104:107], v[136:139], v[214:217], v[104:107]
	v_mfma_f32_16x16x32_bf16 v[92:95], v[128:131], v[224:227], v[92:95]
	v_mfma_f32_16x16x32_bf16 v[88:91], v[136:139], v[224:227], v[88:91]
	v_mfma_f32_16x16x32_bf16 v[76:79], v[128:131], v[232:235], v[76:79]
	v_mfma_f32_16x16x32_bf16 v[72:75], v[136:139], v[232:235], v[72:75]
	v_mfma_f32_16x16x32_bf16 v[124:127], v[132:135], v[210:213], v[124:127]
	v_mfma_f32_16x16x32_bf16 v[120:123], v[140:143], v[210:213], v[120:123]
	v_mfma_f32_16x16x32_bf16 v[108:111], v[132:135], v[218:221], v[108:111]
	v_mfma_f32_16x16x32_bf16 v[104:107], v[140:143], v[218:221], v[104:107]
	v_mfma_f32_16x16x32_bf16 v[92:95], v[132:135], v[228:231], v[92:95]
	v_mfma_f32_16x16x32_bf16 v[88:91], v[140:143], v[228:231], v[88:91]
	v_mfma_f32_16x16x32_bf16 v[76:79], v[132:135], v[236:239], v[76:79]
	v_mfma_f32_16x16x32_bf16 v[72:75], v[140:143], v[236:239], v[72:75]
	s_setprio 0
	s_setprio 1
	v_mfma_f32_16x16x32_bf16 v[116:119], v[174:177], v[196:199], v[116:119]
	v_mfma_f32_16x16x32_bf16 v[112:115], v[188:191], v[196:199], v[112:115]
	v_mfma_f32_16x16x32_bf16 v[100:103], v[174:177], v[214:217], v[100:103]
	v_mfma_f32_16x16x32_bf16 v[96:99], v[188:191], v[214:217], v[96:99]
	v_mfma_f32_16x16x32_bf16 v[84:87], v[174:177], v[224:227], v[84:87]
	v_mfma_f32_16x16x32_bf16 v[80:83], v[188:191], v[224:227], v[80:83]
	v_mfma_f32_16x16x32_bf16 v[68:71], v[174:177], v[232:235], v[68:71]
	v_mfma_f32_16x16x32_bf16 v[64:67], v[188:191], v[232:235], v[64:67]
	v_mfma_f32_16x16x32_bf16 v[116:119], v[184:187], v[210:213], v[116:119]
	v_mfma_f32_16x16x32_bf16 v[112:115], v[192:195], v[210:213], v[112:115]
	v_mfma_f32_16x16x32_bf16 v[100:103], v[184:187], v[218:221], v[100:103]
	v_mfma_f32_16x16x32_bf16 v[96:99], v[192:195], v[218:221], v[96:99]
	v_mfma_f32_16x16x32_bf16 v[84:87], v[184:187], v[228:231], v[84:87]
	v_mfma_f32_16x16x32_bf16 v[80:83], v[192:195], v[228:231], v[80:83]
	v_mfma_f32_16x16x32_bf16 v[68:71], v[184:187], v[236:239], v[68:71]
	v_mfma_f32_16x16x32_bf16 v[64:67], v[192:195], v[236:239], v[64:67]
	s_setprio 0
	s_barrier
	s_add_i32 s62, s83, s8
	v_lshl_add_u64 v[178:179], v[178:179], 0, s[22:23]
	s_mov_b32 m0, s62
	ds_read_b128 v[196:199], v183 offset:49152
	ds_read_b128 v[210:213], v183 offset:50176
	ds_read_b128 v[214:217], v183 offset:51200
	ds_read_b128 v[218:221], v183 offset:52224
	ds_read_b128 v[224:227], v183 offset:53248
	ds_read_b128 v[228:231], v183 offset:54272
	ds_read_b128 v[232:235], v183 offset:55296
	ds_read_b128 v[236:239], v183 offset:56320
	global_load_lds_dwordx4 v[178:179], off
	s_add_i32 m0, s62, 0x2000
	s_add_u32 s44, s44, 0x20080
	v_lshl_add_u64 v[178:179], v[240:241], 0, s[22:23]
	s_addc_u32 s45, s45, 0
	s_add_i32 s62, s84, s8
	global_load_lds_dwordx4 v[178:179], off
	v_lshl_add_u64 v[178:179], s[44:45], 0, v[152:153]
	s_mov_b32 m0, s62
	s_nop 0
	global_load_lds_dwordx4 v[178:179], off
	v_lshl_add_u64 v[178:179], s[44:45], 0, v[144:145]
	s_add_i32 m0, s62, 0x2000
	s_nop 0
	global_load_lds_dwordx4 v[178:179], off
	v_lshl_add_u64 v[178:179], v[242:243], 0, s[22:23]
	s_mov_b32 m0, s69
	s_nop 0
	global_load_lds_dwordx4 v[178:179], off
	v_lshl_add_u64 v[178:179], v[244:245], 0, s[22:23]
	s_mov_b32 m0, s74
	s_nop 0
	global_load_lds_dwordx4 v[178:179], off
	s_waitcnt vmcnt(8)
	s_waitcnt lgkmcnt(0)
	s_setprio 1
	s_barrier
	s_waitcnt lgkmcnt(0)
	v_mfma_f32_16x16x32_bf16 v[60:63], v[128:131], v[196:199], v[60:63]
	v_mfma_f32_16x16x32_bf16 v[56:59], v[136:139], v[196:199], v[56:59]
	v_mfma_f32_16x16x32_bf16 v[44:47], v[128:131], v[214:217], v[44:47]
	v_mfma_f32_16x16x32_bf16 v[40:43], v[136:139], v[214:217], v[40:43]
	v_mfma_f32_16x16x32_bf16 v[28:31], v[128:131], v[224:227], v[28:31]
	v_mfma_f32_16x16x32_bf16 v[24:27], v[136:139], v[224:227], v[24:27]
	v_mfma_f32_16x16x32_bf16 v[12:15], v[128:131], v[232:235], v[12:15]
	v_mfma_f32_16x16x32_bf16 v[8:11], v[136:139], v[232:235], v[8:11]
	v_mfma_f32_16x16x32_bf16 v[60:63], v[132:135], v[210:213], v[60:63]
	v_mfma_f32_16x16x32_bf16 v[56:59], v[140:143], v[210:213], v[56:59]
	v_mfma_f32_16x16x32_bf16 v[44:47], v[132:135], v[218:221], v[44:47]
	v_mfma_f32_16x16x32_bf16 v[40:43], v[140:143], v[218:221], v[40:43]
	v_mfma_f32_16x16x32_bf16 v[28:31], v[132:135], v[228:231], v[28:31]
	v_mfma_f32_16x16x32_bf16 v[24:27], v[140:143], v[228:231], v[24:27]
	v_mfma_f32_16x16x32_bf16 v[12:15], v[132:135], v[236:239], v[12:15]
	v_mfma_f32_16x16x32_bf16 v[8:11], v[140:143], v[236:239], v[8:11]
	s_setprio 0
	s_setprio 1
	v_mfma_f32_16x16x32_bf16 v[52:55], v[174:177], v[196:199], v[52:55]
	v_mfma_f32_16x16x32_bf16 v[48:51], v[188:191], v[196:199], v[48:51]
	v_mfma_f32_16x16x32_bf16 v[36:39], v[174:177], v[214:217], v[36:39]
	v_mfma_f32_16x16x32_bf16 v[32:35], v[188:191], v[214:217], v[32:35]
	v_mfma_f32_16x16x32_bf16 v[20:23], v[174:177], v[224:227], v[20:23]
	v_mfma_f32_16x16x32_bf16 v[16:19], v[188:191], v[224:227], v[16:19]
	v_mfma_f32_16x16x32_bf16 v[4:7], v[174:177], v[232:235], v[4:7]
	v_mfma_f32_16x16x32_bf16 v[0:3], v[188:191], v[232:235], v[0:3]
	v_mfma_f32_16x16x32_bf16 v[52:55], v[184:187], v[210:213], v[52:55]
	v_mfma_f32_16x16x32_bf16 v[48:51], v[192:195], v[210:213], v[48:51]
	v_mfma_f32_16x16x32_bf16 v[36:39], v[184:187], v[218:221], v[36:39]
	v_mfma_f32_16x16x32_bf16 v[32:35], v[192:195], v[218:221], v[32:35]
	v_mfma_f32_16x16x32_bf16 v[20:23], v[184:187], v[228:231], v[20:23]
	v_mfma_f32_16x16x32_bf16 v[16:19], v[192:195], v[228:231], v[16:19]
	v_mfma_f32_16x16x32_bf16 v[4:7], v[184:187], v[236:239], v[4:7]
	v_mfma_f32_16x16x32_bf16 v[0:3], v[192:195], v[236:239], v[0:3]
	s_setprio 0
	s_barrier
	s_add_i32 s82, s82, 2
	s_add_u32 s80, s80, 0x100
	s_addc_u32 s81, s81, 0
	s_add_u32 s60, s60, 0x100
	s_addc_u32 s61, s61, 0
	s_cmp_gt_u32 s82, 5

.LBB0_821:
	s_ashr_i32 s21, s20, 31
	s_lshl_b64 s[48:49], s[20:21], 19
	s_add_u32 s48, s70, s48
	s_addc_u32 s49, s71, s49
	s_and_b64 s[50:51], s[46:47], exec
	s_cselect_b32 s21, s49, s61
	s_cselect_b32 s81, s48, s60
	s_ashr_i32 s19, s18, 31
	s_lshl_b64 s[50:51], s[18:19], 19
	v_readlane_b32 s19, v254, 54
	s_add_u32 s50, s19, s50
	v_readlane_b32 s19, v254, 55
	s_addc_u32 s51, s19, s51
	s_and_b64 s[66:67], s[46:47], exec
	s_cselect_b32 s19, s51, s63
	s_cselect_b32 s82, s50, s62
	s_add_u32 s83, s62, 0x100
	s_addc_u32 s84, s63, 0
	s_add_u32 s60, s60, 0x40080
	s_addc_u32 s61, s61, 0
	s_mov_b32 s85, -2
	s_waitcnt lgkmcnt(0)
	s_add_u32 s62, s60, 0xfffc0080
	s_addc_u32 s63, s61, -1
	s_add_i32 s86, 0, 0x10000
	s_cmp_eq_u32 s85, 12
	s_cselect_b32 s67, s21, s63
	s_cselect_b32 s66, s81, s62
	s_cselect_b32 s63, s19, s84
	s_cselect_b32 s62, s82, s83
	s_add_i32 s89, 0, 0x14000
	v_add_u32_e32 v124, s86, v210
	v_add_u32_e32 v186, s89, v210
	ds_read_b128 v[112:115], v124
	ds_read_b128 v[116:119], v124 offset:1024
	ds_read_b128 v[120:123], v124 offset:2048
	ds_read_b128 v[124:127], v124 offset:3072
	ds_read_b128 v[132:135], v186
	ds_read_b128 v[140:143], v186 offset:1024
	ds_read_b128 v[182:185], v186 offset:2048
	ds_read_b128 v[186:189], v186 offset:3072
	v_lshl_add_u64 v[198:199], s[60:61], 0, v[180:181]
	s_add_i32 m0, s68, 0xc000
	ds_read_b128 v[190:193], v212
	ds_read_b128 v[194:197], v212 offset:1024
	ds_read_b128 v[214:217], v212 offset:2048
	ds_read_b128 v[218:221], v212 offset:3072
	ds_read_b128 v[224:227], v212 offset:4096
	ds_read_b128 v[228:231], v212 offset:5120
	ds_read_b128 v[232:235], v212 offset:6144
	ds_read_b128 v[236:239], v212 offset:7168
	global_load_lds_dwordx4 v[198:199], off
	v_lshl_add_u64 v[198:199], s[60:61], 0, v[178:179]
	s_add_i32 m0, s68, 0xe000
	s_nop 0
	global_load_lds_dwordx4 v[198:199], off
	s_waitcnt vmcnt(8)
	s_waitcnt lgkmcnt(0)
	s_setprio 1
	s_barrier
	s_waitcnt lgkmcnt(0)
	v_mfma_f32_16x16x32_bf16 v[148:151], v[112:115], v[190:193], 0
	v_mfma_f32_16x16x32_bf16 v[144:147], v[120:123], v[190:193], 0
	v_mfma_f32_16x16x32_bf16 v[108:111], v[112:115], v[214:217], 0
	v_mfma_f32_16x16x32_bf16 v[104:107], v[120:123], v[214:217], 0
	v_mfma_f32_16x16x32_bf16 v[92:95], v[112:115], v[224:227], 0
	v_mfma_f32_16x16x32_bf16 v[88:91], v[120:123], v[224:227], 0
	v_mfma_f32_16x16x32_bf16 v[76:79], v[112:115], v[232:235], 0
	v_mfma_f32_16x16x32_bf16 v[72:75], v[120:123], v[232:235], 0
	v_mfma_f32_16x16x32_bf16 v[148:151], v[116:119], v[194:197], v[148:151]
	v_mfma_f32_16x16x32_bf16 v[144:147], v[124:127], v[194:197], v[144:147]
	v_mfma_f32_16x16x32_bf16 v[108:111], v[116:119], v[218:221], v[108:111]
	v_mfma_f32_16x16x32_bf16 v[104:107], v[124:127], v[218:221], v[104:107]
	v_mfma_f32_16x16x32_bf16 v[92:95], v[116:119], v[228:231], v[92:95]
	v_mfma_f32_16x16x32_bf16 v[88:91], v[124:127], v[228:231], v[88:91]
	v_mfma_f32_16x16x32_bf16 v[76:79], v[116:119], v[236:239], v[76:79]
	v_mfma_f32_16x16x32_bf16 v[72:75], v[124:127], v[236:239], v[72:75]
	s_setprio 0
	s_setprio 1
	v_mfma_f32_16x16x32_bf16 v[136:139], v[132:135], v[190:193], 0
	v_mfma_f32_16x16x32_bf16 v[128:131], v[182:185], v[190:193], 0
	v_mfma_f32_16x16x32_bf16 v[100:103], v[132:135], v[214:217], 0
	v_mfma_f32_16x16x32_bf16 v[96:99], v[182:185], v[214:217], 0
	v_mfma_f32_16x16x32_bf16 v[84:87], v[132:135], v[224:227], 0
	v_mfma_f32_16x16x32_bf16 v[80:83], v[182:185], v[224:227], 0
	v_mfma_f32_16x16x32_bf16 v[68:71], v[132:135], v[232:235], 0
	v_mfma_f32_16x16x32_bf16 v[64:67], v[182:185], v[232:235], 0
	v_mfma_f32_16x16x32_bf16 v[136:139], v[140:143], v[194:197], v[136:139]
	v_mfma_f32_16x16x32_bf16 v[128:131], v[186:189], v[194:197], v[128:131]
	v_mfma_f32_16x16x32_bf16 v[100:103], v[140:143], v[218:221], v[100:103]
	v_mfma_f32_16x16x32_bf16 v[96:99], v[186:189], v[218:221], v[96:99]
	v_mfma_f32_16x16x32_bf16 v[84:87], v[140:143], v[228:231], v[84:87]
	v_mfma_f32_16x16x32_bf16 v[80:83], v[186:189], v[228:231], v[80:83]
	v_mfma_f32_16x16x32_bf16 v[68:71], v[140:143], v[236:239], v[68:71]
	v_mfma_f32_16x16x32_bf16 v[64:67], v[186:189], v[236:239], v[64:67]
	s_setprio 0
	s_barrier
	s_add_i32 s86, s86, s59
	v_lshl_add_u64 v[198:199], s[62:63], 0, v[152:153]
	s_mov_b32 m0, s86
	ds_read_b128 v[190:193], v212 offset:16384
	ds_read_b128 v[194:197], v212 offset:17408
	ds_read_b128 v[214:217], v212 offset:18432
	ds_read_b128 v[218:221], v212 offset:19456
	ds_read_b128 v[224:227], v212 offset:20480
	ds_read_b128 v[228:231], v212 offset:21504
	ds_read_b128 v[232:235], v212 offset:22528
	ds_read_b128 v[236:239], v212 offset:23552
	global_load_lds_dwordx4 v[198:199], off
	s_add_i32 m0, s86, 0x2000
	s_add_u32 s86, s62, 0x40000
	v_lshl_add_u64 v[240:241], s[62:63], 0, v[172:173]
	s_addc_u32 s87, s63, 0
	s_add_i32 s89, s89, s59
	global_load_lds_dwordx4 v[240:241], off
	v_lshl_add_u64 v[242:243], s[86:87], 0, v[152:153]
	s_mov_b32 m0, s89
	v_lshl_add_u64 v[244:245], s[66:67], 0, v[174:175]
	global_load_lds_dwordx4 v[242:243], off
	v_lshl_add_u64 v[242:243], s[86:87], 0, v[172:173]
	s_add_i32 m0, s89, 0x2000
	s_nop 0
	global_load_lds_dwordx4 v[242:243], off
	v_lshl_add_u64 v[242:243], s[66:67], 0, v[176:177]
	s_mov_b32 m0, s68
	s_nop 0
	global_load_lds_dwordx4 v[242:243], off
	s_mov_b32 m0, s69
	s_nop 0
	global_load_lds_dwordx4 v[244:245], off
	s_waitcnt vmcnt(8)
	s_waitcnt lgkmcnt(0)
	s_setprio 1
	s_barrier
	s_waitcnt lgkmcnt(0)
	v_mfma_f32_16x16x32_bf16 v[60:63], v[112:115], v[190:193], 0
	v_mfma_f32_16x16x32_bf16 v[56:59], v[120:123], v[190:193], 0
	v_mfma_f32_16x16x32_bf16 v[44:47], v[112:115], v[214:217], 0
	v_mfma_f32_16x16x32_bf16 v[40:43], v[120:123], v[214:217], 0
	v_mfma_f32_16x16x32_bf16 v[28:31], v[112:115], v[224:227], 0
	v_mfma_f32_16x16x32_bf16 v[24:27], v[120:123], v[224:227], 0
	v_mfma_f32_16x16x32_bf16 v[12:15], v[112:115], v[232:235], 0
	v_mfma_f32_16x16x32_bf16 v[8:11], v[120:123], v[232:235], 0
	v_mfma_f32_16x16x32_bf16 v[60:63], v[116:119], v[194:197], v[60:63]
	v_mfma_f32_16x16x32_bf16 v[56:59], v[124:127], v[194:197], v[56:59]
	v_mfma_f32_16x16x32_bf16 v[44:47], v[116:119], v[218:221], v[44:47]
	v_mfma_f32_16x16x32_bf16 v[40:43], v[124:127], v[218:221], v[40:43]
	v_mfma_f32_16x16x32_bf16 v[28:31], v[116:119], v[228:231], v[28:31]
	v_mfma_f32_16x16x32_bf16 v[24:27], v[124:127], v[228:231], v[24:27]
	v_mfma_f32_16x16x32_bf16 v[12:15], v[116:119], v[236:239], v[12:15]
	v_mfma_f32_16x16x32_bf16 v[8:11], v[124:127], v[236:239], v[8:11]
	s_setprio 0
	s_setprio 1
	v_mfma_f32_16x16x32_bf16 v[52:55], v[132:135], v[190:193], 0
	v_mfma_f32_16x16x32_bf16 v[48:51], v[182:185], v[190:193], 0
	v_mfma_f32_16x16x32_bf16 v[36:39], v[132:135], v[214:217], 0
	v_mfma_f32_16x16x32_bf16 v[32:35], v[182:185], v[214:217], 0
	v_mfma_f32_16x16x32_bf16 v[20:23], v[132:135], v[224:227], 0
	v_mfma_f32_16x16x32_bf16 v[16:19], v[182:185], v[224:227], 0
	v_mfma_f32_16x16x32_bf16 v[4:7], v[132:135], v[232:235], 0
	v_mfma_f32_16x16x32_bf16 v[0:3], v[182:185], v[232:235], 0
	v_mfma_f32_16x16x32_bf16 v[52:55], v[140:143], v[194:197], v[52:55]
	v_mfma_f32_16x16x32_bf16 v[48:51], v[186:189], v[194:197], v[48:51]
	v_mfma_f32_16x16x32_bf16 v[36:39], v[140:143], v[218:221], v[36:39]
	v_mfma_f32_16x16x32_bf16 v[32:35], v[186:189], v[218:221], v[32:35]
	v_mfma_f32_16x16x32_bf16 v[20:23], v[140:143], v[228:231], v[20:23]
	v_mfma_f32_16x16x32_bf16 v[16:19], v[186:189], v[228:231], v[16:19]
	v_mfma_f32_16x16x32_bf16 v[4:7], v[140:143], v[236:239], v[4:7]
	v_mfma_f32_16x16x32_bf16 v[0:3], v[186:189], v[236:239], v[0:3]
	s_setprio 0
	s_barrier
	s_add_i32 s86, 0, 0x18000
	s_add_i32 s87, 0, 0x1c000
	v_add_u32_e32 v124, s86, v210
	v_add_u32_e32 v186, s87, v210
	ds_read_b128 v[112:115], v124
	ds_read_b128 v[116:119], v124 offset:1024
	ds_read_b128 v[120:123], v124 offset:2048
	ds_read_b128 v[124:127], v124 offset:3072
	ds_read_b128 v[132:135], v186
	ds_read_b128 v[140:143], v186 offset:1024
	ds_read_b128 v[182:185], v186 offset:2048
	ds_read_b128 v[186:189], v186 offset:3072
	s_add_u32 s66, s66, 0x40000
	s_addc_u32 s67, s67, 0
	s_mov_b32 m0, s74
	v_lshl_add_u64 v[246:247], s[66:67], 0, v[176:177]
	ds_read_b128 v[190:193], v212 offset:32768
	ds_read_b128 v[194:197], v212 offset:33792
	ds_read_b128 v[214:217], v212 offset:34816
	ds_read_b128 v[218:221], v212 offset:35840
	ds_read_b128 v[224:227], v212 offset:36864
	ds_read_b128 v[228:231], v212 offset:37888
	ds_read_b128 v[232:235], v212 offset:38912
	ds_read_b128 v[236:239], v212 offset:39936
	global_load_lds_dwordx4 v[246:247], off
	v_lshl_add_u64 v[246:247], s[66:67], 0, v[174:175]
	s_mov_b32 m0, s75
	s_nop 0
	global_load_lds_dwordx4 v[246:247], off
	s_waitcnt vmcnt(8)
	s_waitcnt lgkmcnt(0)
	s_setprio 1
	s_barrier
	s_waitcnt lgkmcnt(0)
	v_mfma_f32_16x16x32_bf16 v[148:151], v[112:115], v[190:193], v[148:151]
	v_mfma_f32_16x16x32_bf16 v[144:147], v[120:123], v[190:193], v[144:147]
	v_mfma_f32_16x16x32_bf16 v[108:111], v[112:115], v[214:217], v[108:111]
	v_mfma_f32_16x16x32_bf16 v[104:107], v[120:123], v[214:217], v[104:107]
	v_mfma_f32_16x16x32_bf16 v[92:95], v[112:115], v[224:227], v[92:95]
	v_mfma_f32_16x16x32_bf16 v[88:91], v[120:123], v[224:227], v[88:91]
	v_mfma_f32_16x16x32_bf16 v[76:79], v[112:115], v[232:235], v[76:79]
	v_mfma_f32_16x16x32_bf16 v[72:75], v[120:123], v[232:235], v[72:75]
	v_mfma_f32_16x16x32_bf16 v[148:151], v[116:119], v[194:197], v[148:151]
	v_mfma_f32_16x16x32_bf16 v[144:147], v[124:127], v[194:197], v[144:147]
	v_mfma_f32_16x16x32_bf16 v[108:111], v[116:119], v[218:221], v[108:111]
	v_mfma_f32_16x16x32_bf16 v[104:107], v[124:127], v[218:221], v[104:107]
	v_mfma_f32_16x16x32_bf16 v[92:95], v[116:119], v[228:231], v[92:95]
	v_mfma_f32_16x16x32_bf16 v[88:91], v[124:127], v[228:231], v[88:91]
	v_mfma_f32_16x16x32_bf16 v[76:79], v[116:119], v[236:239], v[76:79]
	v_mfma_f32_16x16x32_bf16 v[72:75], v[124:127], v[236:239], v[72:75]
	s_setprio 0
	s_setprio 1
	v_mfma_f32_16x16x32_bf16 v[136:139], v[132:135], v[190:193], v[136:139]
	v_mfma_f32_16x16x32_bf16 v[128:131], v[182:185], v[190:193], v[128:131]
	v_mfma_f32_16x16x32_bf16 v[100:103], v[132:135], v[214:217], v[100:103]
	v_mfma_f32_16x16x32_bf16 v[96:99], v[182:185], v[214:217], v[96:99]
	v_mfma_f32_16x16x32_bf16 v[84:87], v[132:135], v[224:227], v[84:87]
	v_mfma_f32_16x16x32_bf16 v[80:83], v[182:185], v[224:227], v[80:83]
	v_mfma_f32_16x16x32_bf16 v[68:71], v[132:135], v[232:235], v[68:71]
	v_mfma_f32_16x16x32_bf16 v[64:67], v[182:185], v[232:235], v[64:67]
	v_mfma_f32_16x16x32_bf16 v[136:139], v[140:143], v[194:197], v[136:139]
	v_mfma_f32_16x16x32_bf16 v[128:131], v[186:189], v[194:197], v[128:131]
	v_mfma_f32_16x16x32_bf16 v[100:103], v[140:143], v[218:221], v[100:103]
	v_mfma_f32_16x16x32_bf16 v[96:99], v[186:189], v[218:221], v[96:99]
	v_mfma_f32_16x16x32_bf16 v[84:87], v[140:143], v[228:231], v[84:87]
	v_mfma_f32_16x16x32_bf16 v[80:83], v[186:189], v[228:231], v[80:83]
	v_mfma_f32_16x16x32_bf16 v[68:71], v[140:143], v[236:239], v[68:71]
	v_mfma_f32_16x16x32_bf16 v[64:67], v[186:189], v[236:239], v[64:67]
	s_setprio 0
	s_barrier
	s_add_i32 s66, s86, s59
	v_lshl_add_u64 v[198:199], v[198:199], 0, s[22:23]
	s_mov_b32 m0, s66
	ds_read_b128 v[190:193], v212 offset:49152
	ds_read_b128 v[194:197], v212 offset:50176
	ds_read_b128 v[214:217], v212 offset:51200
	ds_read_b128 v[218:221], v212 offset:52224
	ds_read_b128 v[224:227], v212 offset:53248
	ds_read_b128 v[228:231], v212 offset:54272
	ds_read_b128 v[232:235], v212 offset:55296
	ds_read_b128 v[236:239], v212 offset:56320
	global_load_lds_dwordx4 v[198:199], off
	s_add_i32 m0, s66, 0x2000
	s_add_u32 s62, s62, 0x40080
	v_lshl_add_u64 v[198:199], v[240:241], 0, s[22:23]
	s_addc_u32 s63, s63, 0
	s_add_i32 s66, s87, s59
	global_load_lds_dwordx4 v[198:199], off
	v_lshl_add_u64 v[198:199], s[62:63], 0, v[152:153]
	s_mov_b32 m0, s66
	s_nop 0
	global_load_lds_dwordx4 v[198:199], off
	v_lshl_add_u64 v[198:199], s[62:63], 0, v[172:173]
	s_add_i32 m0, s66, 0x2000
	s_nop 0
	global_load_lds_dwordx4 v[198:199], off
	v_lshl_add_u64 v[198:199], v[242:243], 0, s[22:23]
	s_mov_b32 m0, s77
	s_nop 0
	global_load_lds_dwordx4 v[198:199], off
	v_lshl_add_u64 v[198:199], v[244:245], 0, s[22:23]
	s_mov_b32 m0, s78
	s_nop 0
	global_load_lds_dwordx4 v[198:199], off
	s_waitcnt vmcnt(8)
	s_waitcnt lgkmcnt(0)
	s_setprio 1
	s_barrier
	s_waitcnt lgkmcnt(0)
	v_mfma_f32_16x16x32_bf16 v[60:63], v[112:115], v[190:193], v[60:63]
	v_mfma_f32_16x16x32_bf16 v[56:59], v[120:123], v[190:193], v[56:59]
	v_mfma_f32_16x16x32_bf16 v[44:47], v[112:115], v[214:217], v[44:47]
	v_mfma_f32_16x16x32_bf16 v[40:43], v[120:123], v[214:217], v[40:43]
	v_mfma_f32_16x16x32_bf16 v[28:31], v[112:115], v[224:227], v[28:31]
	v_mfma_f32_16x16x32_bf16 v[24:27], v[120:123], v[224:227], v[24:27]
	v_mfma_f32_16x16x32_bf16 v[12:15], v[112:115], v[232:235], v[12:15]
	v_mfma_f32_16x16x32_bf16 v[8:11], v[120:123], v[232:235], v[8:11]
	v_mfma_f32_16x16x32_bf16 v[60:63], v[116:119], v[194:197], v[60:63]
	v_mfma_f32_16x16x32_bf16 v[56:59], v[124:127], v[194:197], v[56:59]
	v_mfma_f32_16x16x32_bf16 v[44:47], v[116:119], v[218:221], v[44:47]
	v_mfma_f32_16x16x32_bf16 v[40:43], v[124:127], v[218:221], v[40:43]
	v_mfma_f32_16x16x32_bf16 v[28:31], v[116:119], v[228:231], v[28:31]
	v_mfma_f32_16x16x32_bf16 v[24:27], v[124:127], v[228:231], v[24:27]
	v_mfma_f32_16x16x32_bf16 v[12:15], v[116:119], v[236:239], v[12:15]
	v_mfma_f32_16x16x32_bf16 v[8:11], v[124:127], v[236:239], v[8:11]
	s_setprio 0
	s_setprio 1
	v_mfma_f32_16x16x32_bf16 v[52:55], v[132:135], v[190:193], v[52:55]
	v_mfma_f32_16x16x32_bf16 v[48:51], v[182:185], v[190:193], v[48:51]
	v_mfma_f32_16x16x32_bf16 v[36:39], v[132:135], v[214:217], v[36:39]
	v_mfma_f32_16x16x32_bf16 v[32:35], v[182:185], v[214:217], v[32:35]
	v_mfma_f32_16x16x32_bf16 v[20:23], v[132:135], v[224:227], v[20:23]
	v_mfma_f32_16x16x32_bf16 v[16:19], v[182:185], v[224:227], v[16:19]
	v_mfma_f32_16x16x32_bf16 v[4:7], v[132:135], v[232:235], v[4:7]
	v_mfma_f32_16x16x32_bf16 v[0:3], v[182:185], v[232:235], v[0:3]
	v_mfma_f32_16x16x32_bf16 v[52:55], v[140:143], v[194:197], v[52:55]
	v_mfma_f32_16x16x32_bf16 v[48:51], v[186:189], v[194:197], v[48:51]
	v_mfma_f32_16x16x32_bf16 v[36:39], v[140:143], v[218:221], v[36:39]
	v_mfma_f32_16x16x32_bf16 v[32:35], v[186:189], v[218:221], v[32:35]
	v_mfma_f32_16x16x32_bf16 v[20:23], v[140:143], v[228:231], v[20:23]
	v_mfma_f32_16x16x32_bf16 v[16:19], v[186:189], v[228:231], v[16:19]
	v_mfma_f32_16x16x32_bf16 v[4:7], v[140:143], v[236:239], v[4:7]
	v_mfma_f32_16x16x32_bf16 v[0:3], v[186:189], v[236:239], v[0:3]
	s_setprio 0
	s_barrier
	s_add_i32 s85, s85, 2
	s_add_u32 s83, s83, 0x100
	s_addc_u32 s84, s84, 0
	s_add_u32 s60, s60, 0x100
	s_addc_u32 s61, s61, 0
	s_cmp_gt_u32 s85, 13
